# BRANCH B operands K-blocked: w_branch and the gate rows of w_in stored [K/32][rows][32] by the prep
# speedup vs baseline: 1.0726x; 1.0194x over previous
; DI void st8(u16* dst, const float (&v)[8]) { *(u32x4*)dst = pack8(v); }
; DI void prep_tile(const float* __restrict__ W, int K, int N, const float* __restrict__ gain, u16* __restrict__ dst, int mode, int tile, char* smem) {
;     ...
;     const int cid = tid + 256 * i, nl = cid >> 3, kc = cid & 7, n = n0 + nl;
;     if (n < N) {
;       float v[8];
; #pragma unroll
;       for (int j = 0; j < 8; ++j) v[j] = Ts[nl * 65 + kc * 8 + j];
;       st8(dst + (size_t)colmap(mode, n) * K + k0 + kc * 8, v);
; DI void phase_prep(const Params& p, char* smem) {
;     ...
;     switch (k) {
;       case 0: W = p.w_in + (size_t)l * 1024 * DIN; K = 1024; N = DIN; gain = p.mix_norm + l * 1024; dst = (u16*)(p.ws + OFF_WIN + l * SZ_WIN); mode = 1; break;
;       case 1: W = p.w_mla_q_b + (size_t)l * 384 * 768; K = 384; N = 768; gain = p.mla_q_a_norm + l * 384; dst = (u16*)(p.ws + OFF_WQB + l * SZ_WQB); mode = 2; break;
;       case 2: W = p.w_mla_kv_b + (size_t)l * 256 * 1024; K = 256; N = 1024; gain = p.mla_kv_a_norm + l * 256; dst = (u16*)(p.ws + OFF_WKVB + l * SZ_WKVB); break;
;       case 3: W = p.w_mem_kv + (size_t)l * 1024 * 1024; K = 1024; N = 1024; gain = p.mem_norm + l * 1024; dst = (u16*)(p.ws + OFF_WMEM + l * SZ_WMEM); break;
;       case 4: case 5: case 6: W = p.w_branch + (size_t)(l * 3 + (k - 4)) * 512 * 1024; K = 512; N = 1024; dst = (u16*)(p.ws + OFF_WBR + (l * 3 + (k - 4)) * SZ_WBR); break;
;       case 7: W = p.w_out + (size_t)l * 1024 * 1024; K = 1024; N = 1024; dst = (u16*)(p.ws + OFF_WOUT + l * SZ_WOUT); break;
;       case 8: W = p.w_ff1 + (size_t)l * 1024 * 4096; K = 1024; N = 4096; gain = p.ffn_norm + l * 1024; dst = (u16*)(p.ws + OFF_WFF1 + l * SZ_WFF1); break;
;       default: W = p.w_ff2 + (size_t)l * 4096 * 1024; K = 4096; N = 1024; dst = (u16*)(p.ws + OFF_WFF2 + l * SZ_WFF2); break;
;     }
.LBB1_41:
	s_mov_b32 s40, 0
	s_cmp_eq_u32 s73, 4
	s_cselect_b32 s40, 0x10000, s40
	s_cmp_eq_u32 s73, 5
	s_cselect_b32 s40, 0x10000, s40
	s_cmp_eq_u32 s73, 6
	s_cselect_b32 s40, 0x10000, s40
	s_cmp_eq_u32 s73, 7
	s_cselect_b32 s40, 0x10000, s40
	s_cmp_eq_u32 s73, 8
	s_cselect_b32 s40, 0x40000, s40
	s_cmp_eq_u32 s73, 9
	s_cselect_b32 s40, 0x10000, s40
	s_cmp_eq_u32 s73, 14
	s_cselect_b32 s40, 0x10000, s40
	s_cmp_eq_u32 s73, 15
	s_cselect_b32 s40, 0x10000, s40
	s_cmp_eq_u32 s73, 16
	s_cselect_b32 s40, 0x10000, s40
	s_cmp_eq_u32 s73, 17
	s_cselect_b32 s40, 0x10000, s40
	s_cmp_eq_u32 s73, 18
	s_cselect_b32 s40, 0x40000, s40
	s_cmp_eq_u32 s73, 19
	s_cselect_b32 s40, 0x10000, s40
	s_cmp_eq_u32 s73, 0
	s_cbranch_scc1 .Lprep_win2
	s_cmp_eq_u32 s73, 10
	s_cbranch_scc1 .Lprep_win2
	s_cmp_eq_u32 s40, 0
	s_cbranch_scc0 .Lprep_blk2
	v_ashrrev_i32_e32 v16, 31, v14
	v_mad_u64_u32 v[14:15], s[40:41], v14, s74, 0
	v_mov_b32_e32 v2, v15
	v_mad_u64_u32 v[16:17], s[40:41], v16, s74, v[2:3]
	v_mov_b32_e32 v15, v16
	v_lshl_add_u64 v[14:15], v[14:15], 1, v[4:5]
	s_branch .Lprep_st2

; DI void st8(u16* dst, const float (&v)[8]) { *(u32x4*)dst = pack8(v); }
; DI int colmap(int mode, int n) {
;   if (mode == 1) return n < 5248 ? n : (n < 5280 ? 8832 + (n - 5248) : n - 32);
;   if (mode == 2) return (n / 96) * 128 + (n % 96);
;   return n;
; }
; DI void prep_tile(const float* __restrict__ W, int K, int N, const float* __restrict__ gain, u16* __restrict__ dst, int mode, int tile, char* smem) {
;     ...
;     const int cid = tid + 256 * i, nl = cid >> 3, kc = cid & 7, n = n0 + nl;
;     if (n < N) {
;       float v[8];
; #pragma unroll
;       for (int j = 0; j < 8; ++j) v[j] = Ts[nl * 65 + kc * 8 + j];
;       st8(dst + (size_t)colmap(mode, n) * K + k0 + kc * 8, v);
.Lprep_win2:
	v_mov_b32_e32 v42, v14
	v_ashrrev_i32_e32 v16, 31, v14
	v_mad_u64_u32 v[14:15], s[40:41], v14, s74, 0
	v_mov_b32_e32 v2, v15
	v_mad_u64_u32 v[16:17], s[40:41], v16, s74, v[2:3]
	v_mov_b32_e32 v15, v16
	v_lshl_add_u64 v[14:15], v[14:15], 1, v[4:5]
	v_subrev_u32_e32 v43, s34, v4
	v_lshrrev_b32_e32 v44, 6, v43
	v_and_b32_e32 v43, 63, v43
	v_lshl_add_u32 v45, v42, 6, v43
	s_mov_b32 s40, 0x5a000
	v_mul_lo_u32 v46, v44, s40
	v_add_u32_e32 v46, v46, v45
	v_lshl_add_u32 v47, v44, 13, v45
	v_add_u32_e32 v47, 0x10b6000, v47
	v_cmp_gt_u32_e32 vcc, 0x1680, v42
	s_nop 1
	v_cndmask_b32_e32 v46, v47, v46, vcc
	s_mov_b32 s40, 0x30000
	v_mul_lo_u32 v47, v44, s40
	v_add_u32_e32 v47, v47, v45
	v_add_u32_e32 v47, 0xae6000, v47
	v_subrev_u32_e32 v43, 0x1680, v42
	v_cmp_gt_u32_e32 vcc, 0xc00, v43
	s_nop 1
	v_cndmask_b32_e32 v46, v46, v47, vcc
	v_mov_b32_e32 v47, 0
	v_lshl_add_u64 v[46:47], s[34:35], 0, v[46:47]
	v_mov_b32_e32 v14, v46
	v_mov_b32_e32 v15, v47
	s_branch .Lprep_st2

; DI void st8(u16* dst, const float (&v)[8]) { *(u32x4*)dst = pack8(v); }
; DI void prep_tile(const float* __restrict__ W, int K, int N, const float* __restrict__ gain, u16* __restrict__ dst, int mode, int tile, char* smem) {
;     ...
;     const int cid = tid + 256 * i, nl = cid >> 3, kc = cid & 7, n = n0 + nl;
;     if (n < N) {
;       float v[8];
; #pragma unroll
;       for (int j = 0; j < 8; ++j) v[j] = Ts[nl * 65 + kc * 8 + j];
;       st8(dst + (size_t)colmap(mode, n) * K + k0 + kc * 8, v);
; DI void phase_prep(const Params& p, char* smem) {
;     ...
;     switch (k) {
;       case 0: W = p.w_in + (size_t)l * 1024 * DIN; K = 1024; N = DIN; gain = p.mix_norm + l * 1024; dst = (u16*)(p.ws + OFF_WIN + l * SZ_WIN); mode = 1; break;
;       case 1: W = p.w_mla_q_b + (size_t)l * 384 * 768; K = 384; N = 768; gain = p.mla_q_a_norm + l * 384; dst = (u16*)(p.ws + OFF_WQB + l * SZ_WQB); mode = 2; break;
;       case 2: W = p.w_mla_kv_b + (size_t)l * 256 * 1024; K = 256; N = 1024; gain = p.mla_kv_a_norm + l * 256; dst = (u16*)(p.ws + OFF_WKVB + l * SZ_WKVB); break;
;       case 3: W = p.w_mem_kv + (size_t)l * 1024 * 1024; K = 1024; N = 1024; gain = p.mem_norm + l * 1024; dst = (u16*)(p.ws + OFF_WMEM + l * SZ_WMEM); break;
;       case 4: case 5: case 6: W = p.w_branch + (size_t)(l * 3 + (k - 4)) * 512 * 1024; K = 512; N = 1024; dst = (u16*)(p.ws + OFF_WBR + (l * 3 + (k - 4)) * SZ_WBR); break;
;       case 7: W = p.w_out + (size_t)l * 1024 * 1024; K = 1024; N = 1024; dst = (u16*)(p.ws + OFF_WOUT + l * SZ_WOUT); break;
;       case 8: W = p.w_ff1 + (size_t)l * 1024 * 4096; K = 1024; N = 4096; gain = p.ffn_norm + l * 1024; dst = (u16*)(p.ws + OFF_WFF1 + l * SZ_WFF1); break;
;       default: W = p.w_ff2 + (size_t)l * 4096 * 1024; K = 4096; N = 1024; dst = (u16*)(p.ws + OFF_WFF2 + l * SZ_WFF2); break;
;     }
.LBB1_122:
	s_mov_b32 s40, 0
	s_cmp_eq_u32 s73, 4
	s_cselect_b32 s40, 0x10000, s40
	s_cmp_eq_u32 s73, 5
	s_cselect_b32 s40, 0x10000, s40
	s_cmp_eq_u32 s73, 6
	s_cselect_b32 s40, 0x10000, s40
	s_cmp_eq_u32 s73, 7
	s_cselect_b32 s40, 0x10000, s40
	s_cmp_eq_u32 s73, 8
	s_cselect_b32 s40, 0x40000, s40
	s_cmp_eq_u32 s73, 9
	s_cselect_b32 s40, 0x10000, s40
	s_cmp_eq_u32 s73, 14
	s_cselect_b32 s40, 0x10000, s40
	s_cmp_eq_u32 s73, 15
	s_cselect_b32 s40, 0x10000, s40
	s_cmp_eq_u32 s73, 16
	s_cselect_b32 s40, 0x10000, s40
	s_cmp_eq_u32 s73, 17
	s_cselect_b32 s40, 0x10000, s40
	s_cmp_eq_u32 s73, 18
	s_cselect_b32 s40, 0x40000, s40
	s_cmp_eq_u32 s73, 19
	s_cselect_b32 s40, 0x10000, s40
	s_cmp_eq_u32 s73, 0
	s_cbranch_scc1 .Lprep_win1
	s_cmp_eq_u32 s73, 10
	s_cbranch_scc1 .Lprep_win1
	s_cmp_eq_u32 s40, 0
	s_cbranch_scc0 .Lprep_blk1
	v_ashrrev_i32_e32 v18, 31, v16
	v_mad_u64_u32 v[16:17], s[40:41], v16, s74, 0
	v_mov_b32_e32 v2, v17
	v_mad_u64_u32 v[18:19], s[40:41], v18, s74, v[2:3]
	v_mov_b32_e32 v17, v18
	v_lshl_add_u64 v[16:17], v[16:17], 1, v[4:5]
	s_branch .Lprep_st1

; DI void st8(u16* dst, const float (&v)[8]) { *(u32x4*)dst = pack8(v); }
; DI int colmap(int mode, int n) {
;   if (mode == 1) return n < 5248 ? n : (n < 5280 ? 8832 + (n - 5248) : n - 32);
;   if (mode == 2) return (n / 96) * 128 + (n % 96);
;   return n;
; }
; DI void prep_tile(const float* __restrict__ W, int K, int N, const float* __restrict__ gain, u16* __restrict__ dst, int mode, int tile, char* smem) {
;     ...
;     const int cid = tid + 256 * i, nl = cid >> 3, kc = cid & 7, n = n0 + nl;
;     if (n < N) {
;       float v[8];
; #pragma unroll
;       for (int j = 0; j < 8; ++j) v[j] = Ts[nl * 65 + kc * 8 + j];
;       st8(dst + (size_t)colmap(mode, n) * K + k0 + kc * 8, v);
.Lprep_win1:
	v_mov_b32_e32 v42, v16
	v_ashrrev_i32_e32 v18, 31, v16
	v_mad_u64_u32 v[16:17], s[40:41], v16, s74, 0
	v_mov_b32_e32 v2, v17
	v_mad_u64_u32 v[18:19], s[40:41], v18, s74, v[2:3]
	v_mov_b32_e32 v17, v18
	v_lshl_add_u64 v[16:17], v[16:17], 1, v[4:5]
	v_subrev_u32_e32 v43, s34, v4
	v_lshrrev_b32_e32 v44, 6, v43
	v_and_b32_e32 v43, 63, v43
	v_lshl_add_u32 v45, v42, 6, v43
	s_mov_b32 s40, 0x5a000
	v_mul_lo_u32 v46, v44, s40
	v_add_u32_e32 v46, v46, v45
	v_lshl_add_u32 v47, v44, 13, v45
	v_add_u32_e32 v47, 0x10b6000, v47
	v_cmp_gt_u32_e32 vcc, 0x1680, v42
	s_nop 1
	v_cndmask_b32_e32 v46, v47, v46, vcc
	s_mov_b32 s40, 0x30000
	v_mul_lo_u32 v47, v44, s40
	v_add_u32_e32 v47, v47, v45
	v_add_u32_e32 v47, 0xae6000, v47
	v_subrev_u32_e32 v43, 0x1680, v42
	v_cmp_gt_u32_e32 vcc, 0xc00, v43
	s_nop 1
	v_cndmask_b32_e32 v46, v46, v47, vcc
	v_mov_b32_e32 v47, 0
	v_lshl_add_u64 v[46:47], s[34:35], 0, v[46:47]
	v_mov_b32_e32 v16, v46
	v_mov_b32_e32 v17, v47
	s_branch .Lprep_st1

; DI int TID() { int t = (int)__builtin_amdgcn_workitem_id_x(); asm volatile("" : "+v"(t)); return t; }
; DI RowSS rowss_load(const float* ps, int m0) { const int tid = TID(); const float* q = ps + (size_t)(m0 + (tid >> 1)) * 16 + (tid & 1) * 8; RowSS r; r.a = *(const f32x4*)q; r.b = *(const f32x4*)(q + 4); return r; }
; DI void tile_branch(const Params& p, int l, int tile, char* smem) {
;     ...
;   const int tid = TID(), lane = tid & 63, w = tid >> 6, wm = w >> 1, wn = w & 1, r32 = lane & 31, hi = lane >> 5;
;   const int mi = tile & (MTN - 1), ni = tile >> MTS; const int m0 = mi * 128, n0 = ni * 128;
;   unsigned upk[2][2][8];
; #pragma unroll
;   for (int a = 0; a < 2; ++a)
; #pragma unroll
;     for (int b = 0; b < 2; ++b)
; #pragma unroll
;       for (int i = 0; i < 8; ++i) upk[a][b][i] = 0u;
;   float* rinv_s = (float*)(smem + SMEM_CS);
;   { const RowSS rss = rowss_load((const float*)(p.ws + OFF_PSIN), m0); rowss_finish(rss, rinv_s); }
; #pragma unroll 1
;   for (int br = 0; br < 3; ++br) {
;     unsigned gpk[2][2][8];
;     {
;       f32x16 accg[2][2]; zero_acc(accg);
;       gemm_main_bf<false, 16>((const u16*)(p.ws + OFF_XB) + (size_t)m0 * 1024, 1024,
;                               (const u16*)(p.ws + OFF_WIN + l * SZ_WIN) + (size_t)(5760 + br * 1024 + n0) * 1024, accg, smem, nullptr);
.LBB1_264:
	s_or_b64 exec, exec, s[26:27]
	v_and_b32_e32 v246, 63, v172
	v_lshrrev_b32_e32 v247, 6, v172
	v_bfe_u32 v166, v246, 4, 2
	v_lshrrev_b32_e32 v167, 1, v166
	v_xor_b32_e32 v166, v166, v167
	v_and_b32_e32 v166, 1, v166
	v_lshl_or_b32 v166, v166, 1, v167
	v_xor_b32_e32 v166, v166, v246
	v_and_b32_e32 v166, 3, v166
	v_lshlrev_b32_e32 v166, 4, v166
	v_lshrrev_b32_e32 v167, 2, v246
	v_lshl_add_u32 v168, v247, 5, v167
	v_lshl_add_u32 v242, v168, 11, v166
	v_add_u32_e32 v243, 0x7c00, v242
	v_lshl_add_u32 v244, v168, 10, v166
	v_add_u32_e32 v245, 0x3c00, v244
	v_lshl_add_u32 v251, v168, 6, v166
	v_readfirstlane_b32 s52, v247
	s_lshl_b32 s52, s52, 11
	s_add_u32 s53, s52, 0x2000
	v_bfe_u32 v166, v246, 2, 2
	v_lshrrev_b32_e32 v167, 1, v166
	v_xor_b32_e32 v166, v166, v167
	v_and_b32_e32 v166, 1, v166
	v_lshl_or_b32 v166, v166, 1, v167
	v_lshrrev_b32_e32 v171, 4, v246
	v_xor_b32_e32 v166, v166, v171
	v_lshlrev_b32_e32 v166, 4, v166
	v_and_b32_e32 v169, 15, v246
	v_lshl_add_u32 v170, v169, 6, v166
	v_lshrrev_b32_e32 v166, 1, v247
	v_and_b32_e32 v167, 1, v247
	v_lshl_add_u32 v240, v166, 12, v170
	v_lshl_add_u32 v241, v167, 12, v170
	v_add_u32_e32 v241, 0x2000, v241
	v_lshl_add_u32 v248, v166, 6, v169
	v_lshlrev_b32_e32 v250, 2, v248
	v_add_u32_e32 v250, 0x12000, v250
	v_lshlrev_b32_e32 v167, 6, v167
	v_lshl_add_u32 v167, v171, 2, v167
	s_and_b32 s12, s17, 0xffffff80
	v_add_u32_e32 v167, s12, v167
	v_add_u32_e32 v168, s16, v248
	v_lshlrev_b32_e32 v249, 11, v168
	v_lshl_add_u32 v249, v167, 1, v249
	s_lshl_b32 s0, s16, 11
	s_add_u32 s44, s34, s0
	s_addc_u32 s45, s35, 0
	s_lshl_b32 s0, s12, 6
	s_add_u32 s0, s0, 0xb40000
	s_add_u32 s46, s93, s0
	s_addc_u32 s47, s42, 0
	s_lshl_b32 s0, s16, 10
	s_add_u32 s48, s18, s96
	s_addc_u32 s49, s19, 0
	s_add_u32 s48, s48, s0
	s_addc_u32 s49, s49, 0
	s_add_u32 s50, s18, s97
	s_addc_u32 s51, s19, 0
	s_add_u32 s50, s50, s24
	s_addc_u32 s51, s51, s25
	s_lshl_b32 s0, s12, 6
	s_add_u32 s50, s50, s0
	s_addc_u32 s51, s51, 0
	s_mov_b64 s[28:29], s[44:45]
	s_mov_b64 s[30:31], s[46:47]
	s_add_u32 m0, s52, 0x0
	s_nop 0
	global_load_lds_dwordx4 v242, s[28:29]
	global_load_lds_dwordx4 v243, s[28:29] offset:1024
	s_add_u32 m0, s53, 0x0
	s_nop 0
	global_load_lds_dwordx4 v251, s[30:31]
	global_load_lds_dwordx4 v251, s[30:31] offset:1024
	s_add_u32 m0, s52, 0x4000
	s_add_u32 s28, s28, 0x40
	s_addc_u32 s29, s29, 0
	global_load_lds_dwordx4 v242, s[28:29]
	global_load_lds_dwordx4 v243, s[28:29] offset:1024
	s_add_u32 m0, s53, 0x4000
	s_add_u32 s30, s30, 0x30000
	s_addc_u32 s31, s31, 0
	global_load_lds_dwordx4 v251, s[30:31]
	global_load_lds_dwordx4 v251, s[30:31] offset:1024
	s_add_u32 m0, s52, 0x8000
	s_add_u32 s28, s28, 0x40
	s_addc_u32 s29, s29, 0
	global_load_lds_dwordx4 v242, s[28:29]
	global_load_lds_dwordx4 v243, s[28:29] offset:1024
	s_add_u32 m0, s53, 0x8000
	s_add_u32 s30, s30, 0x30000
	s_addc_u32 s31, s31, 0
	global_load_lds_dwordx4 v251, s[30:31]
	global_load_lds_dwordx4 v251, s[30:31] offset:1024
	v_mov_b32_e32 v66, 0
	v_mov_b32_e32 v67, 0
	v_mov_b32_e32 v68, 0
	v_mov_b32_e32 v69, 0
	v_mov_b32_e32 v70, 0
	v_mov_b32_e32 v71, 0
	v_mov_b32_e32 v72, 0
	v_mov_b32_e32 v73, 0
	v_mov_b32_e32 v74, 0
	v_mov_b32_e32 v75, 0
	v_mov_b32_e32 v76, 0
	v_mov_b32_e32 v77, 0
	v_mov_b32_e32 v78, 0
	v_mov_b32_e32 v79, 0
	v_mov_b32_e32 v80, 0
	v_mov_b32_e32 v81, 0
	v_mov_b32_e32 v82, 0
	v_mov_b32_e32 v83, 0
	v_mov_b32_e32 v84, 0
	v_mov_b32_e32 v85, 0
	v_mov_b32_e32 v86, 0
	v_mov_b32_e32 v87, 0
	v_mov_b32_e32 v88, 0
	v_mov_b32_e32 v89, 0
	v_mov_b32_e32 v90, 0
	v_mov_b32_e32 v91, 0
	v_mov_b32_e32 v92, 0
	v_mov_b32_e32 v93, 0
	v_mov_b32_e32 v94, 0
	v_mov_b32_e32 v95, 0
	v_mov_b32_e32 v96, 0
	v_mov_b32_e32 v97, 0
	v_mov_b32_e32 v98, 0
	v_mov_b32_e32 v99, 0
	v_mov_b32_e32 v100, 0
	v_mov_b32_e32 v101, 0
	v_mov_b32_e32 v102, 0
	v_mov_b32_e32 v103, 0
	v_mov_b32_e32 v104, 0
	v_mov_b32_e32 v105, 0
	v_mov_b32_e32 v106, 0
	v_mov_b32_e32 v107, 0
	v_mov_b32_e32 v108, 0
	v_mov_b32_e32 v109, 0
	v_mov_b32_e32 v110, 0
	v_mov_b32_e32 v111, 0
	v_mov_b32_e32 v112, 0
	v_mov_b32_e32 v113, 0
	v_mov_b32_e32 v114, 0
	v_mov_b32_e32 v115, 0
	v_mov_b32_e32 v116, 0
	v_mov_b32_e32 v117, 0
	v_mov_b32_e32 v118, 0
	v_mov_b32_e32 v119, 0
	v_mov_b32_e32 v120, 0
	v_mov_b32_e32 v121, 0
	v_mov_b32_e32 v122, 0
	v_mov_b32_e32 v123, 0
	v_mov_b32_e32 v124, 0
	v_mov_b32_e32 v125, 0
	v_mov_b32_e32 v126, 0
	v_mov_b32_e32 v127, 0
	v_mov_b32_e32 v128, 0
	v_mov_b32_e32 v129, 0
	s_mov_b32 s75, 0

; #define BLOAD(A_, B_, kt) do { _Pragma("unroll") for (int i = 0; i < 4; ++i) { \
;     A_[i] = *(const u32x4*)((const char*)Ap + (aoff + (unsigned)(32 * i * lda + (kt) * 64) * 2u)); B_[i] = *(const u32x4*)((const char*)Wt + (woff + (unsigned)(32 * i * K + (kt) * 64) * 2u)); } } while (0)
; #define BLOAD(A_, B_, kt) do { _Pragma("unroll") for (int i = 0; i < 4; ++i) { \
;     A_[i] = *(const u32x4*)((const char*)Ap + (aoff + (unsigned)(32 * i * lda + (kt) * 64) * 2u)); B_[i] = *(const u32x4*)((const char*)Wt + (woff + (unsigned)(32 * i * K + (kt) * 64) * 2u)); } } while (0)
; #define BSTORE(A_, B_, buf) do { _Pragma("unroll") for (int i = 0; i < 4; ++i) { \
;     *(u32x4*)&As[(buf) * GBUF + (srow + 32 * i) * LDT + sc8] = A_[i]; \
;     *(u32x4*)&Bs[(buf) * GBUF + (srow + 32 * i) * LDT + sc8] = B_[i]; } } while (0)
; template <bool ROWNORM, int NK>
; DI void gemm_main_bf(const u16* __restrict__ Ap, int lda, const u16* __restrict__ Wt, f32x16 (&acc)[2][2], char* smem, float* rinv_s) {
;     ...
;   __builtin_amdgcn_s_setprio(0);
;   BLOAD(a0, b0, 0); BLOAD(a1, b1, 1);
;   __syncthreads();
;   BSTORE(a0, b0, 0);
;   BLOAD(a0, b0, 2);
;   __syncthreads();
; #pragma unroll
;   for (int kt = 0; kt < nk; kt += 2) {
;     BCOMP(0);
;     BSTORE(a1, b1, 1);
;     if (kt + 3 < nk) BLOAD(a1, b1, kt + 3);
;     __syncthreads();
;     BCOMP(1);
;     if (kt + 2 < nk) { BSTORE(a0, b0, 0); if (kt + 4 < nk) BLOAD(a0, b0, kt + 4); }
;     __syncthreads();
;   }
.Lbr_gate_k:
	s_waitcnt vmcnt(8)
	s_barrier
	ds_read_b128 v[208:211], v240 offset:0
	ds_read_b128 v[224:227], v241 offset:0
	ds_read_b128 v[228:231], v241 offset:1024
	ds_read_b128 v[232:235], v241 offset:2048
	ds_read_b128 v[236:239], v241 offset:3072
	s_add_u32 m0, s52, 0xc000
	s_add_u32 s28, s28, 0x40
	s_addc_u32 s29, s29, 0
	global_load_lds_dwordx4 v242, s[28:29]
	global_load_lds_dwordx4 v243, s[28:29] offset:1024
	s_add_u32 m0, s53, 0xc000
	s_add_u32 s30, s30, 0x30000
	s_addc_u32 s31, s31, 0
	global_load_lds_dwordx4 v251, s[30:31]
	global_load_lds_dwordx4 v251, s[30:31] offset:1024
	ds_read_b128 v[212:215], v240 offset:1024
	ds_read_b128 v[216:219], v240 offset:2048
	ds_read_b128 v[220:223], v240 offset:3072
	s_waitcnt lgkmcnt(6)
	v_mfma_f32_16x16x32_bf16 v[2:5], v[224:227], v[208:211], v[2:5]
	s_waitcnt lgkmcnt(5)
	v_mfma_f32_16x16x32_bf16 v[6:9], v[228:231], v[208:211], v[6:9]
	s_waitcnt lgkmcnt(4)
	v_mfma_f32_16x16x32_bf16 v[10:13], v[232:235], v[208:211], v[10:13]
	s_waitcnt lgkmcnt(3)
	v_mfma_f32_16x16x32_bf16 v[14:17], v[236:239], v[208:211], v[14:17]
	s_waitcnt lgkmcnt(2)
	v_mfma_f32_16x16x32_bf16 v[18:21], v[224:227], v[212:215], v[18:21]
	v_mfma_f32_16x16x32_bf16 v[22:25], v[228:231], v[212:215], v[22:25]
	v_mfma_f32_16x16x32_bf16 v[26:29], v[232:235], v[212:215], v[26:29]
	v_mfma_f32_16x16x32_bf16 v[30:33], v[236:239], v[212:215], v[30:33]
	s_waitcnt lgkmcnt(1)
	v_mfma_f32_16x16x32_bf16 v[34:37], v[224:227], v[216:219], v[34:37]
	v_mfma_f32_16x16x32_bf16 v[38:41], v[228:231], v[216:219], v[38:41]
	v_mfma_f32_16x16x32_bf16 v[42:45], v[232:235], v[216:219], v[42:45]
	v_mfma_f32_16x16x32_bf16 v[46:49], v[236:239], v[216:219], v[46:49]
	s_waitcnt lgkmcnt(0)
	v_mfma_f32_16x16x32_bf16 v[50:53], v[224:227], v[220:223], v[50:53]
	v_mfma_f32_16x16x32_bf16 v[54:57], v[228:231], v[220:223], v[54:57]
	v_mfma_f32_16x16x32_bf16 v[58:61], v[232:235], v[220:223], v[58:61]
	v_mfma_f32_16x16x32_bf16 v[62:65], v[236:239], v[220:223], v[62:65]
	s_waitcnt vmcnt(8)
	s_barrier
	ds_read_b128 v[208:211], v240 offset:16384
	ds_read_b128 v[224:227], v241 offset:16384
	ds_read_b128 v[228:231], v241 offset:17408
	ds_read_b128 v[232:235], v241 offset:18432
	ds_read_b128 v[236:239], v241 offset:19456
	s_add_u32 m0, s52, 0x0
	s_add_u32 s28, s28, 0x40
	s_addc_u32 s29, s29, 0
	global_load_lds_dwordx4 v242, s[28:29]
	global_load_lds_dwordx4 v243, s[28:29] offset:1024
	s_add_u32 m0, s53, 0x0
	s_add_u32 s30, s30, 0x30000
	s_addc_u32 s31, s31, 0
	global_load_lds_dwordx4 v251, s[30:31]
	global_load_lds_dwordx4 v251, s[30:31] offset:1024
	ds_read_b128 v[212:215], v240 offset:17408
	ds_read_b128 v[216:219], v240 offset:18432
	ds_read_b128 v[220:223], v240 offset:19456
	s_waitcnt lgkmcnt(6)
	v_mfma_f32_16x16x32_bf16 v[2:5], v[224:227], v[208:211], v[2:5]
	s_waitcnt lgkmcnt(5)
	v_mfma_f32_16x16x32_bf16 v[6:9], v[228:231], v[208:211], v[6:9]
	s_waitcnt lgkmcnt(4)
	v_mfma_f32_16x16x32_bf16 v[10:13], v[232:235], v[208:211], v[10:13]
	s_waitcnt lgkmcnt(3)
	v_mfma_f32_16x16x32_bf16 v[14:17], v[236:239], v[208:211], v[14:17]
	s_waitcnt lgkmcnt(2)
	v_mfma_f32_16x16x32_bf16 v[18:21], v[224:227], v[212:215], v[18:21]
	v_mfma_f32_16x16x32_bf16 v[22:25], v[228:231], v[212:215], v[22:25]
	v_mfma_f32_16x16x32_bf16 v[26:29], v[232:235], v[212:215], v[26:29]
	v_mfma_f32_16x16x32_bf16 v[30:33], v[236:239], v[212:215], v[30:33]
	s_waitcnt lgkmcnt(1)
	v_mfma_f32_16x16x32_bf16 v[34:37], v[224:227], v[216:219], v[34:37]
	v_mfma_f32_16x16x32_bf16 v[38:41], v[228:231], v[216:219], v[38:41]
	v_mfma_f32_16x16x32_bf16 v[42:45], v[232:235], v[216:219], v[42:45]
	v_mfma_f32_16x16x32_bf16 v[46:49], v[236:239], v[216:219], v[46:49]
	s_waitcnt lgkmcnt(0)
	v_mfma_f32_16x16x32_bf16 v[50:53], v[224:227], v[220:223], v[50:53]
	v_mfma_f32_16x16x32_bf16 v[54:57], v[228:231], v[220:223], v[54:57]
	v_mfma_f32_16x16x32_bf16 v[58:61], v[232:235], v[220:223], v[58:61]
	v_mfma_f32_16x16x32_bf16 v[62:65], v[236:239], v[220:223], v[62:65]
	s_waitcnt vmcnt(8)
	s_barrier
	ds_read_b128 v[208:211], v240 offset:32768
	ds_read_b128 v[224:227], v241 offset:32768
	ds_read_b128 v[228:231], v241 offset:33792
	ds_read_b128 v[232:235], v241 offset:34816
	ds_read_b128 v[236:239], v241 offset:35840
	s_add_u32 m0, s52, 0x4000
	s_add_u32 s28, s28, 0x40
	s_addc_u32 s29, s29, 0
	global_load_lds_dwordx4 v242, s[28:29]
	global_load_lds_dwordx4 v243, s[28:29] offset:1024
	s_add_u32 m0, s53, 0x4000
	s_add_u32 s30, s30, 0x30000
	s_addc_u32 s31, s31, 0
	global_load_lds_dwordx4 v251, s[30:31]
	global_load_lds_dwordx4 v251, s[30:31] offset:1024
	ds_read_b128 v[212:215], v240 offset:33792
	ds_read_b128 v[216:219], v240 offset:34816
	ds_read_b128 v[220:223], v240 offset:35840
	s_waitcnt lgkmcnt(6)
	v_mfma_f32_16x16x32_bf16 v[2:5], v[224:227], v[208:211], v[2:5]
	s_waitcnt lgkmcnt(5)
	v_mfma_f32_16x16x32_bf16 v[6:9], v[228:231], v[208:211], v[6:9]
	s_waitcnt lgkmcnt(4)
	v_mfma_f32_16x16x32_bf16 v[10:13], v[232:235], v[208:211], v[10:13]
	s_waitcnt lgkmcnt(3)
	v_mfma_f32_16x16x32_bf16 v[14:17], v[236:239], v[208:211], v[14:17]
	s_waitcnt lgkmcnt(2)
	v_mfma_f32_16x16x32_bf16 v[18:21], v[224:227], v[212:215], v[18:21]
	v_mfma_f32_16x16x32_bf16 v[22:25], v[228:231], v[212:215], v[22:25]
	v_mfma_f32_16x16x32_bf16 v[26:29], v[232:235], v[212:215], v[26:29]
	v_mfma_f32_16x16x32_bf16 v[30:33], v[236:239], v[212:215], v[30:33]
	s_waitcnt lgkmcnt(1)
	v_mfma_f32_16x16x32_bf16 v[34:37], v[224:227], v[216:219], v[34:37]
	v_mfma_f32_16x16x32_bf16 v[38:41], v[228:231], v[216:219], v[38:41]
	v_mfma_f32_16x16x32_bf16 v[42:45], v[232:235], v[216:219], v[42:45]
	v_mfma_f32_16x16x32_bf16 v[46:49], v[236:239], v[216:219], v[46:49]
	s_waitcnt lgkmcnt(0)
	v_mfma_f32_16x16x32_bf16 v[50:53], v[224:227], v[220:223], v[50:53]
	v_mfma_f32_16x16x32_bf16 v[54:57], v[228:231], v[220:223], v[54:57]
	v_mfma_f32_16x16x32_bf16 v[58:61], v[232:235], v[220:223], v[58:61]
	v_mfma_f32_16x16x32_bf16 v[62:65], v[236:239], v[220:223], v[62:65]
	s_waitcnt vmcnt(8)
	s_barrier
; #define BLOAD(A_, B_, kt) do { _Pragma("unroll") for (int i = 0; i < 4; ++i) { \
;     A_[i] = *(const u32x4*)((const char*)Ap + (aoff + (unsigned)(32 * i * lda + (kt) * 64) * 2u)); B_[i] = *(const u32x4*)((const char*)Wt + (woff + (unsigned)(32 * i * K + (kt) * 64) * 2u)); } } while (0)
; #define BLOAD(A_, B_, kt) do { _Pragma("unroll") for (int i = 0; i < 4; ++i) { \
;     A_[i] = *(const u32x4*)((const char*)Ap + (aoff + (unsigned)(32 * i * lda + (kt) * 64) * 2u)); B_[i] = *(const u32x4*)((const char*)Wt + (woff + (unsigned)(32 * i * K + (kt) * 64) * 2u)); } } while (0)
; #define BSTORE(A_, B_, buf) do { _Pragma("unroll") for (int i = 0; i < 4; ++i) { \
;     *(u32x4*)&As[(buf) * GBUF + (srow + 32 * i) * LDT + sc8] = A_[i]; \
;     *(u32x4*)&Bs[(buf) * GBUF + (srow + 32 * i) * LDT + sc8] = B_[i]; } } while (0)
; template <bool ROWNORM, int NK>
; DI void gemm_main_bf(const u16* __restrict__ Ap, int lda, const u16* __restrict__ Wt, f32x16 (&acc)[2][2], char* smem, float* rinv_s) {
;     ...
;   __builtin_amdgcn_s_setprio(0);
;   BLOAD(a0, b0, 0); BLOAD(a1, b1, 1);
;   __syncthreads();
;   BSTORE(a0, b0, 0);
;   BLOAD(a0, b0, 2);
;   __syncthreads();
; #pragma unroll
;   for (int kt = 0; kt < nk; kt += 2) {
;     BCOMP(0);
;     BSTORE(a1, b1, 1);
;     if (kt + 3 < nk) BLOAD(a1, b1, kt + 3);
;     __syncthreads();
;     BCOMP(1);
;     if (kt + 2 < nk) { BSTORE(a0, b0, 0); if (kt + 4 < nk) BLOAD(a0, b0, kt + 4); }
;     __syncthreads();
;   }
	ds_read_b128 v[208:211], v240 offset:49152
	ds_read_b128 v[224:227], v241 offset:49152
	ds_read_b128 v[228:231], v241 offset:50176
	ds_read_b128 v[232:235], v241 offset:51200
	ds_read_b128 v[236:239], v241 offset:52224
	s_add_u32 m0, s52, 0x8000
	s_add_u32 s28, s28, 0x40
	s_addc_u32 s29, s29, 0
	global_load_lds_dwordx4 v242, s[28:29]
	global_load_lds_dwordx4 v243, s[28:29] offset:1024
	s_add_u32 m0, s53, 0x8000
	s_add_u32 s30, s30, 0x30000
	s_addc_u32 s31, s31, 0
	global_load_lds_dwordx4 v251, s[30:31]
	global_load_lds_dwordx4 v251, s[30:31] offset:1024
	ds_read_b128 v[212:215], v240 offset:50176
	ds_read_b128 v[216:219], v240 offset:51200
	ds_read_b128 v[220:223], v240 offset:52224
	s_waitcnt lgkmcnt(6)
	v_mfma_f32_16x16x32_bf16 v[2:5], v[224:227], v[208:211], v[2:5]
	s_waitcnt lgkmcnt(5)
	v_mfma_f32_16x16x32_bf16 v[6:9], v[228:231], v[208:211], v[6:9]
	s_waitcnt lgkmcnt(4)
	v_mfma_f32_16x16x32_bf16 v[10:13], v[232:235], v[208:211], v[10:13]
	s_waitcnt lgkmcnt(3)
	v_mfma_f32_16x16x32_bf16 v[14:17], v[236:239], v[208:211], v[14:17]
	s_waitcnt lgkmcnt(2)
	v_mfma_f32_16x16x32_bf16 v[18:21], v[224:227], v[212:215], v[18:21]
	v_mfma_f32_16x16x32_bf16 v[22:25], v[228:231], v[212:215], v[22:25]
	v_mfma_f32_16x16x32_bf16 v[26:29], v[232:235], v[212:215], v[26:29]
	v_mfma_f32_16x16x32_bf16 v[30:33], v[236:239], v[212:215], v[30:33]
	s_waitcnt lgkmcnt(1)
	v_mfma_f32_16x16x32_bf16 v[34:37], v[224:227], v[216:219], v[34:37]
	v_mfma_f32_16x16x32_bf16 v[38:41], v[228:231], v[216:219], v[38:41]
	v_mfma_f32_16x16x32_bf16 v[42:45], v[232:235], v[216:219], v[42:45]
	v_mfma_f32_16x16x32_bf16 v[46:49], v[236:239], v[216:219], v[46:49]
	s_waitcnt lgkmcnt(0)
	v_mfma_f32_16x16x32_bf16 v[50:53], v[224:227], v[220:223], v[50:53]
	v_mfma_f32_16x16x32_bf16 v[54:57], v[228:231], v[220:223], v[54:57]
	v_mfma_f32_16x16x32_bf16 v[58:61], v[232:235], v[220:223], v[58:61]
	v_mfma_f32_16x16x32_bf16 v[62:65], v[236:239], v[220:223], v[62:65]
	s_sub_u32 s74, s74, 1
	s_cmp_lg_u32 s74, 0
	s_cbranch_scc1 .Lbr_gate_k
	s_waitcnt vmcnt(8)
	s_barrier
	ds_read_b128 v[208:211], v240 offset:0
	ds_read_b128 v[224:227], v241 offset:0
	ds_read_b128 v[228:231], v241 offset:1024
	ds_read_b128 v[232:235], v241 offset:2048
	ds_read_b128 v[236:239], v241 offset:3072
	s_add_u32 m0, s52, 0xc000
	s_add_u32 s28, s28, 0x40
	s_addc_u32 s29, s29, 0
	global_load_lds_dwordx4 v242, s[28:29]
	global_load_lds_dwordx4 v243, s[28:29] offset:1024
	s_add_u32 m0, s53, 0xc000
	s_add_u32 s30, s30, 0x30000
	s_addc_u32 s31, s31, 0
	global_load_lds_dwordx4 v251, s[30:31]
	global_load_lds_dwordx4 v251, s[30:31] offset:1024
	ds_read_b128 v[212:215], v240 offset:1024
	ds_read_b128 v[216:219], v240 offset:2048
	ds_read_b128 v[220:223], v240 offset:3072
	s_waitcnt lgkmcnt(6)
	v_mfma_f32_16x16x32_bf16 v[2:5], v[224:227], v[208:211], v[2:5]
	s_waitcnt lgkmcnt(5)
	v_mfma_f32_16x16x32_bf16 v[6:9], v[228:231], v[208:211], v[6:9]
	s_waitcnt lgkmcnt(4)
	v_mfma_f32_16x16x32_bf16 v[10:13], v[232:235], v[208:211], v[10:13]
	s_waitcnt lgkmcnt(3)
	v_mfma_f32_16x16x32_bf16 v[14:17], v[236:239], v[208:211], v[14:17]
	s_waitcnt lgkmcnt(2)
	v_mfma_f32_16x16x32_bf16 v[18:21], v[224:227], v[212:215], v[18:21]
	v_mfma_f32_16x16x32_bf16 v[22:25], v[228:231], v[212:215], v[22:25]
	v_mfma_f32_16x16x32_bf16 v[26:29], v[232:235], v[212:215], v[26:29]
	v_mfma_f32_16x16x32_bf16 v[30:33], v[236:239], v[212:215], v[30:33]
	s_waitcnt lgkmcnt(1)
	v_mfma_f32_16x16x32_bf16 v[34:37], v[224:227], v[216:219], v[34:37]
	v_mfma_f32_16x16x32_bf16 v[38:41], v[228:231], v[216:219], v[38:41]
	v_mfma_f32_16x16x32_bf16 v[42:45], v[232:235], v[216:219], v[42:45]
	v_mfma_f32_16x16x32_bf16 v[46:49], v[236:239], v[216:219], v[46:49]
	s_waitcnt lgkmcnt(0)
	v_mfma_f32_16x16x32_bf16 v[50:53], v[224:227], v[220:223], v[50:53]
	v_mfma_f32_16x16x32_bf16 v[54:57], v[228:231], v[220:223], v[54:57]
	v_mfma_f32_16x16x32_bf16 v[58:61], v[232:235], v[220:223], v[58:61]
	v_mfma_f32_16x16x32_bf16 v[62:65], v[236:239], v[220:223], v[62:65]
	s_waitcnt vmcnt(8)
	s_barrier
	ds_read_b128 v[208:211], v240 offset:16384
	ds_read_b128 v[224:227], v241 offset:16384
	ds_read_b128 v[228:231], v241 offset:17408
	ds_read_b128 v[232:235], v241 offset:18432
	ds_read_b128 v[236:239], v241 offset:19456
	ds_read_b128 v[212:215], v240 offset:17408
	ds_read_b128 v[216:219], v240 offset:18432
	ds_read_b128 v[220:223], v240 offset:19456
	s_waitcnt lgkmcnt(6)
	v_mfma_f32_16x16x32_bf16 v[2:5], v[224:227], v[208:211], v[2:5]
	s_waitcnt lgkmcnt(5)
	v_mfma_f32_16x16x32_bf16 v[6:9], v[228:231], v[208:211], v[6:9]
	s_waitcnt lgkmcnt(4)
	v_mfma_f32_16x16x32_bf16 v[10:13], v[232:235], v[208:211], v[10:13]
	s_waitcnt lgkmcnt(3)
	v_mfma_f32_16x16x32_bf16 v[14:17], v[236:239], v[208:211], v[14:17]
	s_waitcnt lgkmcnt(2)
	v_mfma_f32_16x16x32_bf16 v[18:21], v[224:227], v[212:215], v[18:21]
	v_mfma_f32_16x16x32_bf16 v[22:25], v[228:231], v[212:215], v[22:25]
	v_mfma_f32_16x16x32_bf16 v[26:29], v[232:235], v[212:215], v[26:29]
	v_mfma_f32_16x16x32_bf16 v[30:33], v[236:239], v[212:215], v[30:33]
	s_waitcnt lgkmcnt(1)
	v_mfma_f32_16x16x32_bf16 v[34:37], v[224:227], v[216:219], v[34:37]
	v_mfma_f32_16x16x32_bf16 v[38:41], v[228:231], v[216:219], v[38:41]
	v_mfma_f32_16x16x32_bf16 v[42:45], v[232:235], v[216:219], v[42:45]
	v_mfma_f32_16x16x32_bf16 v[46:49], v[236:239], v[216:219], v[46:49]
	s_waitcnt lgkmcnt(0)
	v_mfma_f32_16x16x32_bf16 v[50:53], v[224:227], v[220:223], v[50:53]
	v_mfma_f32_16x16x32_bf16 v[54:57], v[228:231], v[220:223], v[54:57]
	v_mfma_f32_16x16x32_bf16 v[58:61], v[232:235], v[220:223], v[58:61]
	v_mfma_f32_16x16x32_bf16 v[62:65], v[236:239], v[220:223], v[62:65]
	s_waitcnt vmcnt(4)
	s_barrier
; DI unsigned pk2(float a, float b) { f2_t v = {a, b}; bf2_t r = __builtin_convertvector(v, bf2_t); return __builtin_bit_cast(unsigned, r); }
; #define BLOAD(A_, B_, kt) do { _Pragma("unroll") for (int i = 0; i < 4; ++i) { \
;     A_[i] = *(const u32x4*)((const char*)Ap + (aoff + (unsigned)(32 * i * lda + (kt) * 64) * 2u)); B_[i] = *(const u32x4*)((const char*)Wt + (woff + (unsigned)(32 * i * K + (kt) * 64) * 2u)); } } while (0)
; #define BLOAD(A_, B_, kt) do { _Pragma("unroll") for (int i = 0; i < 4; ++i) { \
;     A_[i] = *(const u32x4*)((const char*)Ap + (aoff + (unsigned)(32 * i * lda + (kt) * 64) * 2u)); B_[i] = *(const u32x4*)((const char*)Wt + (woff + (unsigned)(32 * i * K + (kt) * 64) * 2u)); } } while (0)
; template <bool ROWNORM, int NK>
; DI void gemm_main_bf(const u16* __restrict__ Ap, int lda, const u16* __restrict__ Wt, f32x16 (&acc)[2][2], char* smem, float* rinv_s) {
;     ...
; #pragma unroll
;   for (int kt = 0; kt < nk; kt += 2) {
;     BCOMP(0);
;     BSTORE(a1, b1, 1);
;     if (kt + 3 < nk) BLOAD(a1, b1, kt + 3);
;     __syncthreads();
;     BCOMP(1);
;     if (kt + 2 < nk) { BSTORE(a0, b0, 0); if (kt + 4 < nk) BLOAD(a0, b0, kt + 4); }
;     __syncthreads();
;   }
; DI void tile_branch(const Params& p, int l, int tile, char* smem) {
;     ...
; #pragma unroll
;       for (int mt = 0; mt < 2; ++mt)
; #pragma unroll
;         for (int g4 = 0; g4 < 4; ++g4) {
;           const f32x4 r4 = *(const f32x4*)&rinv_s[wm * 64 + mt * 32 + 8 * g4 + 4 * hi];
; #pragma unroll
;           for (int nt = 0; nt < 2; ++nt) {
;             const float s0 = 1.f / (1.f + __expf(-accg[mt][nt][4 * g4 + 0] * r4[0])), s1 = 1.f / (1.f + __expf(-accg[mt][nt][4 * g4 + 1] * r4[1]));
;             const float s2 = 1.f / (1.f + __expf(-accg[mt][nt][4 * g4 + 2] * r4[2])), s3 = 1.f / (1.f + __expf(-accg[mt][nt][4 * g4 + 3] * r4[3]));
;             gpk[mt][nt][2 * g4] = pk2(s0, s1); gpk[mt][nt][2 * g4 + 1] = pk2(s2, s3);
;           }
;         }
;     }
;     f32x16 acc[2][2]; zero_acc(acc);
;     gemm_main_bf<false, 8>((const u16*)(p.ws + OFF_BR) + (size_t)(br * CT + m0) * 512, 512,
;                             (const u16*)(p.ws + OFF_WBR + (l * 3 + br) * SZ_WBR) + (size_t)n0 * 512, acc, smem, nullptr);
	ds_read_b128 v[208:211], v240 offset:32768
	ds_read_b128 v[224:227], v241 offset:32768
	ds_read_b128 v[228:231], v241 offset:33792
	ds_read_b128 v[232:235], v241 offset:34816
	ds_read_b128 v[236:239], v241 offset:35840
	ds_read_b128 v[212:215], v240 offset:33792
	ds_read_b128 v[216:219], v240 offset:34816
	ds_read_b128 v[220:223], v240 offset:35840
	s_waitcnt lgkmcnt(6)
	v_mfma_f32_16x16x32_bf16 v[2:5], v[224:227], v[208:211], v[2:5]
	s_waitcnt lgkmcnt(5)
	v_mfma_f32_16x16x32_bf16 v[6:9], v[228:231], v[208:211], v[6:9]
	s_waitcnt lgkmcnt(4)
	v_mfma_f32_16x16x32_bf16 v[10:13], v[232:235], v[208:211], v[10:13]
	s_waitcnt lgkmcnt(3)
	v_mfma_f32_16x16x32_bf16 v[14:17], v[236:239], v[208:211], v[14:17]
	s_waitcnt lgkmcnt(2)
	v_mfma_f32_16x16x32_bf16 v[18:21], v[224:227], v[212:215], v[18:21]
	v_mfma_f32_16x16x32_bf16 v[22:25], v[228:231], v[212:215], v[22:25]
	v_mfma_f32_16x16x32_bf16 v[26:29], v[232:235], v[212:215], v[26:29]
	v_mfma_f32_16x16x32_bf16 v[30:33], v[236:239], v[212:215], v[30:33]
	s_waitcnt lgkmcnt(1)
	v_mfma_f32_16x16x32_bf16 v[34:37], v[224:227], v[216:219], v[34:37]
	v_mfma_f32_16x16x32_bf16 v[38:41], v[228:231], v[216:219], v[38:41]
	v_mfma_f32_16x16x32_bf16 v[42:45], v[232:235], v[216:219], v[42:45]
	v_mfma_f32_16x16x32_bf16 v[46:49], v[236:239], v[216:219], v[46:49]
	s_waitcnt lgkmcnt(0)
	v_mfma_f32_16x16x32_bf16 v[50:53], v[224:227], v[220:223], v[50:53]
	v_mfma_f32_16x16x32_bf16 v[54:57], v[228:231], v[220:223], v[54:57]
	v_mfma_f32_16x16x32_bf16 v[58:61], v[232:235], v[220:223], v[58:61]
	v_mfma_f32_16x16x32_bf16 v[62:65], v[236:239], v[220:223], v[62:65]
	s_waitcnt vmcnt(0)
	s_barrier
	ds_read_b128 v[208:211], v240 offset:49152
	ds_read_b128 v[224:227], v241 offset:49152
	ds_read_b128 v[228:231], v241 offset:50176
	ds_read_b128 v[232:235], v241 offset:51200
	ds_read_b128 v[236:239], v241 offset:52224
	ds_read_b128 v[212:215], v240 offset:50176
	ds_read_b128 v[216:219], v240 offset:51200
	ds_read_b128 v[220:223], v240 offset:52224
	s_waitcnt lgkmcnt(6)
	v_mfma_f32_16x16x32_bf16 v[2:5], v[224:227], v[208:211], v[2:5]
	s_waitcnt lgkmcnt(5)
	v_mfma_f32_16x16x32_bf16 v[6:9], v[228:231], v[208:211], v[6:9]
	s_waitcnt lgkmcnt(4)
	v_mfma_f32_16x16x32_bf16 v[10:13], v[232:235], v[208:211], v[10:13]
	s_waitcnt lgkmcnt(3)
	v_mfma_f32_16x16x32_bf16 v[14:17], v[236:239], v[208:211], v[14:17]
	s_waitcnt lgkmcnt(2)
	v_mfma_f32_16x16x32_bf16 v[18:21], v[224:227], v[212:215], v[18:21]
	v_mfma_f32_16x16x32_bf16 v[22:25], v[228:231], v[212:215], v[22:25]
	v_mfma_f32_16x16x32_bf16 v[26:29], v[232:235], v[212:215], v[26:29]
	v_mfma_f32_16x16x32_bf16 v[30:33], v[236:239], v[212:215], v[30:33]
	s_waitcnt lgkmcnt(1)
	v_mfma_f32_16x16x32_bf16 v[34:37], v[224:227], v[216:219], v[34:37]
	v_mfma_f32_16x16x32_bf16 v[38:41], v[228:231], v[216:219], v[38:41]
	v_mfma_f32_16x16x32_bf16 v[42:45], v[232:235], v[216:219], v[42:45]
	v_mfma_f32_16x16x32_bf16 v[46:49], v[236:239], v[216:219], v[46:49]
	s_waitcnt lgkmcnt(0)
	v_mfma_f32_16x16x32_bf16 v[50:53], v[224:227], v[220:223], v[50:53]
	v_mfma_f32_16x16x32_bf16 v[54:57], v[228:231], v[220:223], v[54:57]
	v_mfma_f32_16x16x32_bf16 v[58:61], v[232:235], v[220:223], v[58:61]
	v_mfma_f32_16x16x32_bf16 v[62:65], v[236:239], v[220:223], v[62:65]
	s_mov_b64 s[28:29], s[48:49]
	s_mov_b64 s[30:31], s[50:51]
	s_add_u32 m0, s52, 0x0
	s_nop 0
	global_load_lds_dwordx4 v244, s[28:29]
	global_load_lds_dwordx4 v245, s[28:29] offset:1024
	s_add_u32 m0, s53, 0x0
	s_nop 0
	global_load_lds_dwordx4 v251, s[30:31]
	global_load_lds_dwordx4 v251, s[30:31] offset:1024
	s_add_u32 m0, s52, 0x4000
	s_add_u32 s28, s28, 0x40
	s_addc_u32 s29, s29, 0
	global_load_lds_dwordx4 v244, s[28:29]
	global_load_lds_dwordx4 v245, s[28:29] offset:1024
	s_add_u32 m0, s53, 0x4000
	s_add_u32 s30, s30, 0x10000
	s_addc_u32 s31, s31, 0
	global_load_lds_dwordx4 v251, s[30:31]
	global_load_lds_dwordx4 v251, s[30:31] offset:1024
	s_add_u32 m0, s52, 0x8000
	s_add_u32 s28, s28, 0x40
	s_addc_u32 s29, s29, 0
	global_load_lds_dwordx4 v244, s[28:29]
	global_load_lds_dwordx4 v245, s[28:29] offset:1024
	s_add_u32 m0, s53, 0x8000
	s_add_u32 s30, s30, 0x10000
	s_addc_u32 s31, s31, 0
	global_load_lds_dwordx4 v251, s[30:31]
	global_load_lds_dwordx4 v251, s[30:31] offset:1024
	ds_read_b32 v162, v250 offset:0
	ds_read_b32 v163, v250 offset:64
	ds_read_b32 v164, v250 offset:128
	ds_read_b32 v165, v250 offset:192
	s_waitcnt lgkmcnt(0)
; DI unsigned pk2(float a, float b) { f2_t v = {a, b}; bf2_t r = __builtin_convertvector(v, bf2_t); return __builtin_bit_cast(unsigned, r); }
; DI void tile_branch(const Params& p, int l, int tile, char* smem) {
;     ...
; #pragma unroll
;       for (int mt = 0; mt < 2; ++mt)
; #pragma unroll
;         for (int g4 = 0; g4 < 4; ++g4) {
;           const f32x4 r4 = *(const f32x4*)&rinv_s[wm * 64 + mt * 32 + 8 * g4 + 4 * hi];
; #pragma unroll
;           for (int nt = 0; nt < 2; ++nt) {
;             const float s0 = 1.f / (1.f + __expf(-accg[mt][nt][4 * g4 + 0] * r4[0])), s1 = 1.f / (1.f + __expf(-accg[mt][nt][4 * g4 + 1] * r4[1]));
;             const float s2 = 1.f / (1.f + __expf(-accg[mt][nt][4 * g4 + 2] * r4[2])), s3 = 1.f / (1.f + __expf(-accg[mt][nt][4 * g4 + 3] * r4[3]));
;             gpk[mt][nt][2 * g4] = pk2(s0, s1); gpk[mt][nt][2 * g4 + 1] = pk2(s2, s3);
;           }
;         }
	v_mul_f32_e32 v162, 0xbfb8aa3b, v162
	v_mul_f32_e32 v163, 0xbfb8aa3b, v163
	v_mul_f32_e32 v164, 0xbfb8aa3b, v164
	v_mul_f32_e32 v165, 0xbfb8aa3b, v165
	v_mul_f32_e32 v166, v162, v2
	v_mul_f32_e32 v167, v162, v3
	v_mul_f32_e32 v168, v162, v4
	v_mul_f32_e32 v169, v162, v5
	v_exp_f32_e32 v166, v166
	v_exp_f32_e32 v167, v167
	v_exp_f32_e32 v168, v168
	v_exp_f32_e32 v169, v169
	v_add_f32_e32 v166, 1.0, v166
	v_add_f32_e32 v167, 1.0, v167
	v_add_f32_e32 v168, 1.0, v168
	v_add_f32_e32 v169, 1.0, v169
	v_rcp_f32_e32 v166, v166
	v_rcp_f32_e32 v167, v167
	v_rcp_f32_e32 v168, v168
	v_rcp_f32_e32 v169, v169
	v_cvt_pk_bf16_f32 v130, v166, v167
	v_cvt_pk_bf16_f32 v131, v168, v169
	v_mul_f32_e32 v166, v162, v6
	v_mul_f32_e32 v167, v162, v7
	v_mul_f32_e32 v168, v162, v8
	v_mul_f32_e32 v169, v162, v9
	v_exp_f32_e32 v166, v166
	v_exp_f32_e32 v167, v167
	v_exp_f32_e32 v168, v168
	v_exp_f32_e32 v169, v169
	v_add_f32_e32 v166, 1.0, v166
	v_add_f32_e32 v167, 1.0, v167
	v_add_f32_e32 v168, 1.0, v168
	v_add_f32_e32 v169, 1.0, v169
	v_rcp_f32_e32 v166, v166
	v_rcp_f32_e32 v167, v167
	v_rcp_f32_e32 v168, v168
	v_rcp_f32_e32 v169, v169
	v_cvt_pk_bf16_f32 v132, v166, v167
	v_cvt_pk_bf16_f32 v133, v168, v169
	v_mul_f32_e32 v166, v162, v10
	v_mul_f32_e32 v167, v162, v11
	v_mul_f32_e32 v168, v162, v12
	v_mul_f32_e32 v169, v162, v13
	v_exp_f32_e32 v166, v166
	v_exp_f32_e32 v167, v167
	v_exp_f32_e32 v168, v168
	v_exp_f32_e32 v169, v169
	v_add_f32_e32 v166, 1.0, v166
	v_add_f32_e32 v167, 1.0, v167
	v_add_f32_e32 v168, 1.0, v168
	v_add_f32_e32 v169, 1.0, v169
	v_rcp_f32_e32 v166, v166
	v_rcp_f32_e32 v167, v167
	v_rcp_f32_e32 v168, v168
	v_rcp_f32_e32 v169, v169
	v_cvt_pk_bf16_f32 v134, v166, v167
	v_cvt_pk_bf16_f32 v135, v168, v169
	v_mul_f32_e32 v166, v162, v14
	v_mul_f32_e32 v167, v162, v15
	v_mul_f32_e32 v168, v162, v16
	v_mul_f32_e32 v169, v162, v17
	v_exp_f32_e32 v166, v166
	v_exp_f32_e32 v167, v167
	v_exp_f32_e32 v168, v168
	v_exp_f32_e32 v169, v169
	v_add_f32_e32 v166, 1.0, v166
	v_add_f32_e32 v167, 1.0, v167
	v_add_f32_e32 v168, 1.0, v168
	v_add_f32_e32 v169, 1.0, v169
	v_rcp_f32_e32 v166, v166
	v_rcp_f32_e32 v167, v167
	v_rcp_f32_e32 v168, v168
	v_rcp_f32_e32 v169, v169
	v_cvt_pk_bf16_f32 v136, v166, v167
	v_cvt_pk_bf16_f32 v137, v168, v169
	v_mul_f32_e32 v166, v163, v18
	v_mul_f32_e32 v167, v163, v19
	v_mul_f32_e32 v168, v163, v20
	v_mul_f32_e32 v169, v163, v21
	v_exp_f32_e32 v166, v166
	v_exp_f32_e32 v167, v167
	v_exp_f32_e32 v168, v168
	v_exp_f32_e32 v169, v169
	v_add_f32_e32 v166, 1.0, v166
	v_add_f32_e32 v167, 1.0, v167
	v_add_f32_e32 v168, 1.0, v168
	v_add_f32_e32 v169, 1.0, v169
	v_rcp_f32_e32 v166, v166
	v_rcp_f32_e32 v167, v167
	v_rcp_f32_e32 v168, v168
	v_rcp_f32_e32 v169, v169
	v_cvt_pk_bf16_f32 v138, v166, v167
	v_cvt_pk_bf16_f32 v139, v168, v169
	v_mul_f32_e32 v166, v163, v22
	v_mul_f32_e32 v167, v163, v23
	v_mul_f32_e32 v168, v163, v24
	v_mul_f32_e32 v169, v163, v25
	v_exp_f32_e32 v166, v166
	v_exp_f32_e32 v167, v167
	v_exp_f32_e32 v168, v168
	v_exp_f32_e32 v169, v169
	v_add_f32_e32 v166, 1.0, v166
	v_add_f32_e32 v167, 1.0, v167
	v_add_f32_e32 v168, 1.0, v168
	v_add_f32_e32 v169, 1.0, v169
	v_rcp_f32_e32 v166, v166
	v_rcp_f32_e32 v167, v167
	v_rcp_f32_e32 v168, v168
	v_rcp_f32_e32 v169, v169
	v_cvt_pk_bf16_f32 v140, v166, v167
	v_cvt_pk_bf16_f32 v141, v168, v169
	v_mul_f32_e32 v166, v163, v26
	v_mul_f32_e32 v167, v163, v27
	v_mul_f32_e32 v168, v163, v28
	v_mul_f32_e32 v169, v163, v29
	v_exp_f32_e32 v166, v166
	v_exp_f32_e32 v167, v167
	v_exp_f32_e32 v168, v168
	v_exp_f32_e32 v169, v169
	v_add_f32_e32 v166, 1.0, v166
	v_add_f32_e32 v167, 1.0, v167
	v_add_f32_e32 v168, 1.0, v168
	v_add_f32_e32 v169, 1.0, v169
	v_rcp_f32_e32 v166, v166
	v_rcp_f32_e32 v167, v167
	v_rcp_f32_e32 v168, v168
	v_rcp_f32_e32 v169, v169
	v_cvt_pk_bf16_f32 v142, v166, v167
	v_cvt_pk_bf16_f32 v143, v168, v169
	v_mul_f32_e32 v166, v163, v30
	v_mul_f32_e32 v167, v163, v31
	v_mul_f32_e32 v168, v163, v32
	v_mul_f32_e32 v169, v163, v33
	v_exp_f32_e32 v166, v166
	v_exp_f32_e32 v167, v167
	v_exp_f32_e32 v168, v168
	v_exp_f32_e32 v169, v169
	v_add_f32_e32 v166, 1.0, v166
	v_add_f32_e32 v167, 1.0, v167
	v_add_f32_e32 v168, 1.0, v168
	v_add_f32_e32 v169, 1.0, v169
	v_rcp_f32_e32 v166, v166
	v_rcp_f32_e32 v167, v167
	v_rcp_f32_e32 v168, v168
	v_rcp_f32_e32 v169, v169
	v_cvt_pk_bf16_f32 v144, v166, v167
	v_cvt_pk_bf16_f32 v145, v168, v169
	v_mul_f32_e32 v166, v164, v34
	v_mul_f32_e32 v167, v164, v35
	v_mul_f32_e32 v168, v164, v36
	v_mul_f32_e32 v169, v164, v37
	v_exp_f32_e32 v166, v166
	v_exp_f32_e32 v167, v167
	v_exp_f32_e32 v168, v168
	v_exp_f32_e32 v169, v169
	v_add_f32_e32 v166, 1.0, v166
	v_add_f32_e32 v167, 1.0, v167
	v_add_f32_e32 v168, 1.0, v168
	v_add_f32_e32 v169, 1.0, v169
	v_rcp_f32_e32 v166, v166
	v_rcp_f32_e32 v167, v167
	v_rcp_f32_e32 v168, v168
	v_rcp_f32_e32 v169, v169
	v_cvt_pk_bf16_f32 v146, v166, v167
	v_cvt_pk_bf16_f32 v147, v168, v169
	v_mul_f32_e32 v166, v164, v38
	v_mul_f32_e32 v167, v164, v39
	v_mul_f32_e32 v168, v164, v40
	v_mul_f32_e32 v169, v164, v41
	v_exp_f32_e32 v166, v166
	v_exp_f32_e32 v167, v167
	v_exp_f32_e32 v168, v168
	v_exp_f32_e32 v169, v169
	v_add_f32_e32 v166, 1.0, v166
	v_add_f32_e32 v167, 1.0, v167
	v_add_f32_e32 v168, 1.0, v168
	v_add_f32_e32 v169, 1.0, v169
	v_rcp_f32_e32 v166, v166
	v_rcp_f32_e32 v167, v167
	v_rcp_f32_e32 v168, v168
	v_rcp_f32_e32 v169, v169
	v_cvt_pk_bf16_f32 v148, v166, v167
	v_cvt_pk_bf16_f32 v149, v168, v169
	v_mul_f32_e32 v166, v164, v42
	v_mul_f32_e32 v167, v164, v43
	v_mul_f32_e32 v168, v164, v44
	v_mul_f32_e32 v169, v164, v45
	v_exp_f32_e32 v166, v166
	v_exp_f32_e32 v167, v167
	v_exp_f32_e32 v168, v168
	v_exp_f32_e32 v169, v169
; DI unsigned pk2(float a, float b) { f2_t v = {a, b}; bf2_t r = __builtin_convertvector(v, bf2_t); return __builtin_bit_cast(unsigned, r); }
; DI void tile_branch(const Params& p, int l, int tile, char* smem) {
;     ...
; #pragma unroll
;       for (int mt = 0; mt < 2; ++mt)
; #pragma unroll
;         for (int g4 = 0; g4 < 4; ++g4) {
;           const f32x4 r4 = *(const f32x4*)&rinv_s[wm * 64 + mt * 32 + 8 * g4 + 4 * hi];
; #pragma unroll
;           for (int nt = 0; nt < 2; ++nt) {
;             const float s0 = 1.f / (1.f + __expf(-accg[mt][nt][4 * g4 + 0] * r4[0])), s1 = 1.f / (1.f + __expf(-accg[mt][nt][4 * g4 + 1] * r4[1]));
;             const float s2 = 1.f / (1.f + __expf(-accg[mt][nt][4 * g4 + 2] * r4[2])), s3 = 1.f / (1.f + __expf(-accg[mt][nt][4 * g4 + 3] * r4[3]));
;             gpk[mt][nt][2 * g4] = pk2(s0, s1); gpk[mt][nt][2 * g4 + 1] = pk2(s2, s3);
;           }
;         }
;     }
;     f32x16 acc[2][2]; zero_acc(acc);
	v_add_f32_e32 v166, 1.0, v166
	v_add_f32_e32 v167, 1.0, v167
	v_add_f32_e32 v168, 1.0, v168
	v_add_f32_e32 v169, 1.0, v169
	v_rcp_f32_e32 v166, v166
	v_rcp_f32_e32 v167, v167
	v_rcp_f32_e32 v168, v168
	v_rcp_f32_e32 v169, v169
	v_cvt_pk_bf16_f32 v150, v166, v167
	v_cvt_pk_bf16_f32 v151, v168, v169
	v_mul_f32_e32 v166, v164, v46
	v_mul_f32_e32 v167, v164, v47
	v_mul_f32_e32 v168, v164, v48
	v_mul_f32_e32 v169, v164, v49
	v_exp_f32_e32 v166, v166
	v_exp_f32_e32 v167, v167
	v_exp_f32_e32 v168, v168
	v_exp_f32_e32 v169, v169
	v_add_f32_e32 v166, 1.0, v166
	v_add_f32_e32 v167, 1.0, v167
	v_add_f32_e32 v168, 1.0, v168
	v_add_f32_e32 v169, 1.0, v169
	v_rcp_f32_e32 v166, v166
	v_rcp_f32_e32 v167, v167
	v_rcp_f32_e32 v168, v168
	v_rcp_f32_e32 v169, v169
	v_cvt_pk_bf16_f32 v152, v166, v167
	v_cvt_pk_bf16_f32 v153, v168, v169
	v_mul_f32_e32 v166, v165, v50
	v_mul_f32_e32 v167, v165, v51
	v_mul_f32_e32 v168, v165, v52
	v_mul_f32_e32 v169, v165, v53
	v_exp_f32_e32 v166, v166
	v_exp_f32_e32 v167, v167
	v_exp_f32_e32 v168, v168
	v_exp_f32_e32 v169, v169
	v_add_f32_e32 v166, 1.0, v166
	v_add_f32_e32 v167, 1.0, v167
	v_add_f32_e32 v168, 1.0, v168
	v_add_f32_e32 v169, 1.0, v169
	v_rcp_f32_e32 v166, v166
	v_rcp_f32_e32 v167, v167
	v_rcp_f32_e32 v168, v168
	v_rcp_f32_e32 v169, v169
	v_cvt_pk_bf16_f32 v154, v166, v167
	v_cvt_pk_bf16_f32 v155, v168, v169
	v_mul_f32_e32 v166, v165, v54
	v_mul_f32_e32 v167, v165, v55
	v_mul_f32_e32 v168, v165, v56
	v_mul_f32_e32 v169, v165, v57
	v_exp_f32_e32 v166, v166
	v_exp_f32_e32 v167, v167
	v_exp_f32_e32 v168, v168
	v_exp_f32_e32 v169, v169
	v_add_f32_e32 v166, 1.0, v166
	v_add_f32_e32 v167, 1.0, v167
	v_add_f32_e32 v168, 1.0, v168
	v_add_f32_e32 v169, 1.0, v169
	v_rcp_f32_e32 v166, v166
	v_rcp_f32_e32 v167, v167
	v_rcp_f32_e32 v168, v168
	v_rcp_f32_e32 v169, v169
	v_cvt_pk_bf16_f32 v156, v166, v167
	v_cvt_pk_bf16_f32 v157, v168, v169
	v_mul_f32_e32 v166, v165, v58
	v_mul_f32_e32 v167, v165, v59
	v_mul_f32_e32 v168, v165, v60
	v_mul_f32_e32 v169, v165, v61
	v_exp_f32_e32 v166, v166
	v_exp_f32_e32 v167, v167
	v_exp_f32_e32 v168, v168
	v_exp_f32_e32 v169, v169
	v_add_f32_e32 v166, 1.0, v166
	v_add_f32_e32 v167, 1.0, v167
	v_add_f32_e32 v168, 1.0, v168
	v_add_f32_e32 v169, 1.0, v169
	v_rcp_f32_e32 v166, v166
	v_rcp_f32_e32 v167, v167
	v_rcp_f32_e32 v168, v168
	v_rcp_f32_e32 v169, v169
	v_cvt_pk_bf16_f32 v158, v166, v167
	v_cvt_pk_bf16_f32 v159, v168, v169
	v_mul_f32_e32 v166, v165, v62
	v_mul_f32_e32 v167, v165, v63
	v_mul_f32_e32 v168, v165, v64
	v_mul_f32_e32 v169, v165, v65
	v_exp_f32_e32 v166, v166
	v_exp_f32_e32 v167, v167
	v_exp_f32_e32 v168, v168
	v_exp_f32_e32 v169, v169
	v_add_f32_e32 v166, 1.0, v166
	v_add_f32_e32 v167, 1.0, v167
	v_add_f32_e32 v168, 1.0, v168
	v_add_f32_e32 v169, 1.0, v169
	v_rcp_f32_e32 v166, v166
	v_rcp_f32_e32 v167, v167
	v_rcp_f32_e32 v168, v168
	v_rcp_f32_e32 v169, v169
	v_cvt_pk_bf16_f32 v160, v166, v167
	v_cvt_pk_bf16_f32 v161, v168, v169
	v_mov_b32_e32 v2, 0
	v_mov_b32_e32 v3, 0
	v_mov_b32_e32 v4, 0
	v_mov_b32_e32 v5, 0
	v_mov_b32_e32 v6, 0
	v_mov_b32_e32 v7, 0
	v_mov_b32_e32 v8, 0
	v_mov_b32_e32 v9, 0
	v_mov_b32_e32 v10, 0
	v_mov_b32_e32 v11, 0
	v_mov_b32_e32 v12, 0
	v_mov_b32_e32 v13, 0
	v_mov_b32_e32 v14, 0
	v_mov_b32_e32 v15, 0
	v_mov_b32_e32 v16, 0
	v_mov_b32_e32 v17, 0
	v_mov_b32_e32 v18, 0
	v_mov_b32_e32 v19, 0
	v_mov_b32_e32 v20, 0
	v_mov_b32_e32 v21, 0
	v_mov_b32_e32 v22, 0
	v_mov_b32_e32 v23, 0
	v_mov_b32_e32 v24, 0
	v_mov_b32_e32 v25, 0
	v_mov_b32_e32 v26, 0
	v_mov_b32_e32 v27, 0
	v_mov_b32_e32 v28, 0
	v_mov_b32_e32 v29, 0
	v_mov_b32_e32 v30, 0
	v_mov_b32_e32 v31, 0
	v_mov_b32_e32 v32, 0
	v_mov_b32_e32 v33, 0
	v_mov_b32_e32 v34, 0
	v_mov_b32_e32 v35, 0
	v_mov_b32_e32 v36, 0
	v_mov_b32_e32 v37, 0
	v_mov_b32_e32 v38, 0
	v_mov_b32_e32 v39, 0
	v_mov_b32_e32 v40, 0
	v_mov_b32_e32 v41, 0
	v_mov_b32_e32 v42, 0
	v_mov_b32_e32 v43, 0
	v_mov_b32_e32 v44, 0
	v_mov_b32_e32 v45, 0
	v_mov_b32_e32 v46, 0
	v_mov_b32_e32 v47, 0
	v_mov_b32_e32 v48, 0
	v_mov_b32_e32 v49, 0
	v_mov_b32_e32 v50, 0
	v_mov_b32_e32 v51, 0
	v_mov_b32_e32 v52, 0
	v_mov_b32_e32 v53, 0
	v_mov_b32_e32 v54, 0
	v_mov_b32_e32 v55, 0
	v_mov_b32_e32 v56, 0
	v_mov_b32_e32 v57, 0
	v_mov_b32_e32 v58, 0
	v_mov_b32_e32 v59, 0
	v_mov_b32_e32 v60, 0
	v_mov_b32_e32 v61, 0
	v_mov_b32_e32 v62, 0
	v_mov_b32_e32 v63, 0
	v_mov_b32_e32 v64, 0
	v_mov_b32_e32 v65, 0
	s_mov_b32 s74, 3
; #define BLOAD(A_, B_, kt) do { _Pragma("unroll") for (int i = 0; i < 4; ++i) { \
;     A_[i] = *(const u32x4*)((const char*)Ap + (aoff + (unsigned)(32 * i * lda + (kt) * 64) * 2u)); B_[i] = *(const u32x4*)((const char*)Wt + (woff + (unsigned)(32 * i * K + (kt) * 64) * 2u)); } } while (0)
; #define BLOAD(A_, B_, kt) do { _Pragma("unroll") for (int i = 0; i < 4; ++i) { \
;     A_[i] = *(const u32x4*)((const char*)Ap + (aoff + (unsigned)(32 * i * lda + (kt) * 64) * 2u)); B_[i] = *(const u32x4*)((const char*)Wt + (woff + (unsigned)(32 * i * K + (kt) * 64) * 2u)); } } while (0)
; #define BSTORE(A_, B_, buf) do { _Pragma("unroll") for (int i = 0; i < 4; ++i) { \
;     *(u32x4*)&As[(buf) * GBUF + (srow + 32 * i) * LDT + sc8] = A_[i]; \
;     *(u32x4*)&Bs[(buf) * GBUF + (srow + 32 * i) * LDT + sc8] = B_[i]; } } while (0)
; template <bool ROWNORM, int NK>
; DI void gemm_main_bf(const u16* __restrict__ Ap, int lda, const u16* __restrict__ Wt, f32x16 (&acc)[2][2], char* smem, float* rinv_s) {
;     ...
;   __builtin_amdgcn_s_setprio(0);
;   BLOAD(a0, b0, 0); BLOAD(a1, b1, 1);
;   __syncthreads();
;   BSTORE(a0, b0, 0);
;   BLOAD(a0, b0, 2);
;   __syncthreads();
; #pragma unroll
;   for (int kt = 0; kt < nk; kt += 2) {
;     BCOMP(0);
;     BSTORE(a1, b1, 1);
;     if (kt + 3 < nk) BLOAD(a1, b1, kt + 3);
;     __syncthreads();
;     BCOMP(1);
;     if (kt + 2 < nk) { BSTORE(a0, b0, 0); if (kt + 4 < nk) BLOAD(a0, b0, kt + 4); }
;     __syncthreads();
;   }
.Lbr_proj_k:
	s_waitcnt vmcnt(8)
	s_barrier
	ds_read_b128 v[208:211], v240 offset:0
	ds_read_b128 v[224:227], v241 offset:0
	ds_read_b128 v[228:231], v241 offset:1024
	ds_read_b128 v[232:235], v241 offset:2048
	ds_read_b128 v[236:239], v241 offset:3072
	s_add_u32 m0, s52, 0xc000
	s_add_u32 s28, s28, 0x40
	s_addc_u32 s29, s29, 0
	global_load_lds_dwordx4 v244, s[28:29]
	global_load_lds_dwordx4 v245, s[28:29] offset:1024
	s_add_u32 m0, s53, 0xc000
	s_add_u32 s30, s30, 0x10000
	s_addc_u32 s31, s31, 0
	global_load_lds_dwordx4 v251, s[30:31]
	global_load_lds_dwordx4 v251, s[30:31] offset:1024
	ds_read_b128 v[212:215], v240 offset:1024
	ds_read_b128 v[216:219], v240 offset:2048
	ds_read_b128 v[220:223], v240 offset:3072
	s_waitcnt lgkmcnt(6)
	v_mfma_f32_16x16x32_bf16 v[2:5], v[224:227], v[208:211], v[2:5]
	s_waitcnt lgkmcnt(5)
	v_mfma_f32_16x16x32_bf16 v[6:9], v[228:231], v[208:211], v[6:9]
	s_waitcnt lgkmcnt(4)
	v_mfma_f32_16x16x32_bf16 v[10:13], v[232:235], v[208:211], v[10:13]
	s_waitcnt lgkmcnt(3)
	v_mfma_f32_16x16x32_bf16 v[14:17], v[236:239], v[208:211], v[14:17]
	s_waitcnt lgkmcnt(2)
	v_mfma_f32_16x16x32_bf16 v[18:21], v[224:227], v[212:215], v[18:21]
	v_mfma_f32_16x16x32_bf16 v[22:25], v[228:231], v[212:215], v[22:25]
	v_mfma_f32_16x16x32_bf16 v[26:29], v[232:235], v[212:215], v[26:29]
	v_mfma_f32_16x16x32_bf16 v[30:33], v[236:239], v[212:215], v[30:33]
	s_waitcnt lgkmcnt(1)
	v_mfma_f32_16x16x32_bf16 v[34:37], v[224:227], v[216:219], v[34:37]
	v_mfma_f32_16x16x32_bf16 v[38:41], v[228:231], v[216:219], v[38:41]
	v_mfma_f32_16x16x32_bf16 v[42:45], v[232:235], v[216:219], v[42:45]
	v_mfma_f32_16x16x32_bf16 v[46:49], v[236:239], v[216:219], v[46:49]
	s_waitcnt lgkmcnt(0)
	v_mfma_f32_16x16x32_bf16 v[50:53], v[224:227], v[220:223], v[50:53]
	v_mfma_f32_16x16x32_bf16 v[54:57], v[228:231], v[220:223], v[54:57]
	v_mfma_f32_16x16x32_bf16 v[58:61], v[232:235], v[220:223], v[58:61]
	v_mfma_f32_16x16x32_bf16 v[62:65], v[236:239], v[220:223], v[62:65]
	s_waitcnt vmcnt(8)
	s_barrier
	ds_read_b128 v[208:211], v240 offset:16384
	ds_read_b128 v[224:227], v241 offset:16384
	ds_read_b128 v[228:231], v241 offset:17408
	ds_read_b128 v[232:235], v241 offset:18432
	ds_read_b128 v[236:239], v241 offset:19456
	s_add_u32 m0, s52, 0x0
	s_add_u32 s28, s28, 0x40
	s_addc_u32 s29, s29, 0
	global_load_lds_dwordx4 v244, s[28:29]
	global_load_lds_dwordx4 v245, s[28:29] offset:1024
	s_add_u32 m0, s53, 0x0
	s_add_u32 s30, s30, 0x10000
	s_addc_u32 s31, s31, 0
	global_load_lds_dwordx4 v251, s[30:31]
	global_load_lds_dwordx4 v251, s[30:31] offset:1024
	ds_read_b128 v[212:215], v240 offset:17408
	ds_read_b128 v[216:219], v240 offset:18432
	ds_read_b128 v[220:223], v240 offset:19456
	s_waitcnt lgkmcnt(6)
	v_mfma_f32_16x16x32_bf16 v[2:5], v[224:227], v[208:211], v[2:5]
	s_waitcnt lgkmcnt(5)
	v_mfma_f32_16x16x32_bf16 v[6:9], v[228:231], v[208:211], v[6:9]
	s_waitcnt lgkmcnt(4)
	v_mfma_f32_16x16x32_bf16 v[10:13], v[232:235], v[208:211], v[10:13]
	s_waitcnt lgkmcnt(3)
	v_mfma_f32_16x16x32_bf16 v[14:17], v[236:239], v[208:211], v[14:17]
	s_waitcnt lgkmcnt(2)
	v_mfma_f32_16x16x32_bf16 v[18:21], v[224:227], v[212:215], v[18:21]
	v_mfma_f32_16x16x32_bf16 v[22:25], v[228:231], v[212:215], v[22:25]
	v_mfma_f32_16x16x32_bf16 v[26:29], v[232:235], v[212:215], v[26:29]
	v_mfma_f32_16x16x32_bf16 v[30:33], v[236:239], v[212:215], v[30:33]
	s_waitcnt lgkmcnt(1)
	v_mfma_f32_16x16x32_bf16 v[34:37], v[224:227], v[216:219], v[34:37]
	v_mfma_f32_16x16x32_bf16 v[38:41], v[228:231], v[216:219], v[38:41]
	v_mfma_f32_16x16x32_bf16 v[42:45], v[232:235], v[216:219], v[42:45]
	v_mfma_f32_16x16x32_bf16 v[46:49], v[236:239], v[216:219], v[46:49]
	s_waitcnt lgkmcnt(0)
	v_mfma_f32_16x16x32_bf16 v[50:53], v[224:227], v[220:223], v[50:53]
	v_mfma_f32_16x16x32_bf16 v[54:57], v[228:231], v[220:223], v[54:57]
	v_mfma_f32_16x16x32_bf16 v[58:61], v[232:235], v[220:223], v[58:61]
	v_mfma_f32_16x16x32_bf16 v[62:65], v[236:239], v[220:223], v[62:65]
	s_waitcnt vmcnt(8)
	s_barrier
	ds_read_b128 v[208:211], v240 offset:32768
	ds_read_b128 v[224:227], v241 offset:32768
	ds_read_b128 v[228:231], v241 offset:33792
	ds_read_b128 v[232:235], v241 offset:34816
	ds_read_b128 v[236:239], v241 offset:35840
	s_add_u32 m0, s52, 0x4000
	s_add_u32 s28, s28, 0x40
	s_addc_u32 s29, s29, 0
	global_load_lds_dwordx4 v244, s[28:29]
	global_load_lds_dwordx4 v245, s[28:29] offset:1024
	s_add_u32 m0, s53, 0x4000
	s_add_u32 s30, s30, 0x10000
	s_addc_u32 s31, s31, 0
	global_load_lds_dwordx4 v251, s[30:31]
	global_load_lds_dwordx4 v251, s[30:31] offset:1024
	ds_read_b128 v[212:215], v240 offset:33792
	ds_read_b128 v[216:219], v240 offset:34816
	ds_read_b128 v[220:223], v240 offset:35840
	s_waitcnt lgkmcnt(6)
	v_mfma_f32_16x16x32_bf16 v[2:5], v[224:227], v[208:211], v[2:5]
	s_waitcnt lgkmcnt(5)
	v_mfma_f32_16x16x32_bf16 v[6:9], v[228:231], v[208:211], v[6:9]
	s_waitcnt lgkmcnt(4)
	v_mfma_f32_16x16x32_bf16 v[10:13], v[232:235], v[208:211], v[10:13]
	s_waitcnt lgkmcnt(3)
	v_mfma_f32_16x16x32_bf16 v[14:17], v[236:239], v[208:211], v[14:17]
	s_waitcnt lgkmcnt(2)
	v_mfma_f32_16x16x32_bf16 v[18:21], v[224:227], v[212:215], v[18:21]
	v_mfma_f32_16x16x32_bf16 v[22:25], v[228:231], v[212:215], v[22:25]
	v_mfma_f32_16x16x32_bf16 v[26:29], v[232:235], v[212:215], v[26:29]
	v_mfma_f32_16x16x32_bf16 v[30:33], v[236:239], v[212:215], v[30:33]
	s_waitcnt lgkmcnt(1)
	v_mfma_f32_16x16x32_bf16 v[34:37], v[224:227], v[216:219], v[34:37]
	v_mfma_f32_16x16x32_bf16 v[38:41], v[228:231], v[216:219], v[38:41]
	v_mfma_f32_16x16x32_bf16 v[42:45], v[232:235], v[216:219], v[42:45]
	v_mfma_f32_16x16x32_bf16 v[46:49], v[236:239], v[216:219], v[46:49]
	s_waitcnt lgkmcnt(0)
	v_mfma_f32_16x16x32_bf16 v[50:53], v[224:227], v[220:223], v[50:53]
	v_mfma_f32_16x16x32_bf16 v[54:57], v[228:231], v[220:223], v[54:57]
	v_mfma_f32_16x16x32_bf16 v[58:61], v[232:235], v[220:223], v[58:61]
	v_mfma_f32_16x16x32_bf16 v[62:65], v[236:239], v[220:223], v[62:65]
	s_waitcnt vmcnt(8)
	s_barrier
; #define BLOAD(A_, B_, kt) do { _Pragma("unroll") for (int i = 0; i < 4; ++i) { \
;     A_[i] = *(const u32x4*)((const char*)Ap + (aoff + (unsigned)(32 * i * lda + (kt) * 64) * 2u)); B_[i] = *(const u32x4*)((const char*)Wt + (woff + (unsigned)(32 * i * K + (kt) * 64) * 2u)); } } while (0)
; #define BLOAD(A_, B_, kt) do { _Pragma("unroll") for (int i = 0; i < 4; ++i) { \
;     A_[i] = *(const u32x4*)((const char*)Ap + (aoff + (unsigned)(32 * i * lda + (kt) * 64) * 2u)); B_[i] = *(const u32x4*)((const char*)Wt + (woff + (unsigned)(32 * i * K + (kt) * 64) * 2u)); } } while (0)
; #define BSTORE(A_, B_, buf) do { _Pragma("unroll") for (int i = 0; i < 4; ++i) { \
;     *(u32x4*)&As[(buf) * GBUF + (srow + 32 * i) * LDT + sc8] = A_[i]; \
;     *(u32x4*)&Bs[(buf) * GBUF + (srow + 32 * i) * LDT + sc8] = B_[i]; } } while (0)
; template <bool ROWNORM, int NK>
; DI void gemm_main_bf(const u16* __restrict__ Ap, int lda, const u16* __restrict__ Wt, f32x16 (&acc)[2][2], char* smem, float* rinv_s) {
;     ...
;   __builtin_amdgcn_s_setprio(0);
;   BLOAD(a0, b0, 0); BLOAD(a1, b1, 1);
;   __syncthreads();
;   BSTORE(a0, b0, 0);
;   BLOAD(a0, b0, 2);
;   __syncthreads();
; #pragma unroll
;   for (int kt = 0; kt < nk; kt += 2) {
;     BCOMP(0);
;     BSTORE(a1, b1, 1);
;     if (kt + 3 < nk) BLOAD(a1, b1, kt + 3);
;     __syncthreads();
;     BCOMP(1);
;     if (kt + 2 < nk) { BSTORE(a0, b0, 0); if (kt + 4 < nk) BLOAD(a0, b0, kt + 4); }
;     __syncthreads();
;   }
	ds_read_b128 v[208:211], v240 offset:49152
	ds_read_b128 v[224:227], v241 offset:49152
	ds_read_b128 v[228:231], v241 offset:50176
	ds_read_b128 v[232:235], v241 offset:51200
	ds_read_b128 v[236:239], v241 offset:52224
	s_add_u32 m0, s52, 0x8000
	s_add_u32 s28, s28, 0x40
	s_addc_u32 s29, s29, 0
	global_load_lds_dwordx4 v244, s[28:29]
	global_load_lds_dwordx4 v245, s[28:29] offset:1024
	s_add_u32 m0, s53, 0x8000
	s_add_u32 s30, s30, 0x10000
	s_addc_u32 s31, s31, 0
	global_load_lds_dwordx4 v251, s[30:31]
	global_load_lds_dwordx4 v251, s[30:31] offset:1024
	ds_read_b128 v[212:215], v240 offset:50176
	ds_read_b128 v[216:219], v240 offset:51200
	ds_read_b128 v[220:223], v240 offset:52224
	s_waitcnt lgkmcnt(6)
	v_mfma_f32_16x16x32_bf16 v[2:5], v[224:227], v[208:211], v[2:5]
	s_waitcnt lgkmcnt(5)
	v_mfma_f32_16x16x32_bf16 v[6:9], v[228:231], v[208:211], v[6:9]
	s_waitcnt lgkmcnt(4)
	v_mfma_f32_16x16x32_bf16 v[10:13], v[232:235], v[208:211], v[10:13]
	s_waitcnt lgkmcnt(3)
	v_mfma_f32_16x16x32_bf16 v[14:17], v[236:239], v[208:211], v[14:17]
	s_waitcnt lgkmcnt(2)
	v_mfma_f32_16x16x32_bf16 v[18:21], v[224:227], v[212:215], v[18:21]
	v_mfma_f32_16x16x32_bf16 v[22:25], v[228:231], v[212:215], v[22:25]
	v_mfma_f32_16x16x32_bf16 v[26:29], v[232:235], v[212:215], v[26:29]
	v_mfma_f32_16x16x32_bf16 v[30:33], v[236:239], v[212:215], v[30:33]
	s_waitcnt lgkmcnt(1)
	v_mfma_f32_16x16x32_bf16 v[34:37], v[224:227], v[216:219], v[34:37]
	v_mfma_f32_16x16x32_bf16 v[38:41], v[228:231], v[216:219], v[38:41]
	v_mfma_f32_16x16x32_bf16 v[42:45], v[232:235], v[216:219], v[42:45]
	v_mfma_f32_16x16x32_bf16 v[46:49], v[236:239], v[216:219], v[46:49]
	s_waitcnt lgkmcnt(0)
	v_mfma_f32_16x16x32_bf16 v[50:53], v[224:227], v[220:223], v[50:53]
	v_mfma_f32_16x16x32_bf16 v[54:57], v[228:231], v[220:223], v[54:57]
	v_mfma_f32_16x16x32_bf16 v[58:61], v[232:235], v[220:223], v[58:61]
	v_mfma_f32_16x16x32_bf16 v[62:65], v[236:239], v[220:223], v[62:65]
	s_sub_u32 s74, s74, 1
	s_cmp_lg_u32 s74, 0
	s_cbranch_scc1 .Lbr_proj_k
	s_waitcnt vmcnt(8)
	s_barrier
	ds_read_b128 v[208:211], v240 offset:0
	ds_read_b128 v[224:227], v241 offset:0
	ds_read_b128 v[228:231], v241 offset:1024
	ds_read_b128 v[232:235], v241 offset:2048
	ds_read_b128 v[236:239], v241 offset:3072
	s_add_u32 m0, s52, 0xc000
	s_add_u32 s28, s28, 0x40
	s_addc_u32 s29, s29, 0
	global_load_lds_dwordx4 v244, s[28:29]
	global_load_lds_dwordx4 v245, s[28:29] offset:1024
	s_add_u32 m0, s53, 0xc000
	s_add_u32 s30, s30, 0x10000
	s_addc_u32 s31, s31, 0
	global_load_lds_dwordx4 v251, s[30:31]
	global_load_lds_dwordx4 v251, s[30:31] offset:1024
	ds_read_b128 v[212:215], v240 offset:1024
	ds_read_b128 v[216:219], v240 offset:2048
	ds_read_b128 v[220:223], v240 offset:3072
	s_waitcnt lgkmcnt(6)
	v_mfma_f32_16x16x32_bf16 v[2:5], v[224:227], v[208:211], v[2:5]
	s_waitcnt lgkmcnt(5)
	v_mfma_f32_16x16x32_bf16 v[6:9], v[228:231], v[208:211], v[6:9]
	s_waitcnt lgkmcnt(4)
	v_mfma_f32_16x16x32_bf16 v[10:13], v[232:235], v[208:211], v[10:13]
	s_waitcnt lgkmcnt(3)
	v_mfma_f32_16x16x32_bf16 v[14:17], v[236:239], v[208:211], v[14:17]
	s_waitcnt lgkmcnt(2)
	v_mfma_f32_16x16x32_bf16 v[18:21], v[224:227], v[212:215], v[18:21]
	v_mfma_f32_16x16x32_bf16 v[22:25], v[228:231], v[212:215], v[22:25]
	v_mfma_f32_16x16x32_bf16 v[26:29], v[232:235], v[212:215], v[26:29]
	v_mfma_f32_16x16x32_bf16 v[30:33], v[236:239], v[212:215], v[30:33]
	s_waitcnt lgkmcnt(1)
	v_mfma_f32_16x16x32_bf16 v[34:37], v[224:227], v[216:219], v[34:37]
	v_mfma_f32_16x16x32_bf16 v[38:41], v[228:231], v[216:219], v[38:41]
	v_mfma_f32_16x16x32_bf16 v[42:45], v[232:235], v[216:219], v[42:45]
	v_mfma_f32_16x16x32_bf16 v[46:49], v[236:239], v[216:219], v[46:49]
	s_waitcnt lgkmcnt(0)
	v_mfma_f32_16x16x32_bf16 v[50:53], v[224:227], v[220:223], v[50:53]
	v_mfma_f32_16x16x32_bf16 v[54:57], v[228:231], v[220:223], v[54:57]
	v_mfma_f32_16x16x32_bf16 v[58:61], v[232:235], v[220:223], v[58:61]
	v_mfma_f32_16x16x32_bf16 v[62:65], v[236:239], v[220:223], v[62:65]
	s_waitcnt vmcnt(8)
	s_barrier
	ds_read_b128 v[208:211], v240 offset:16384
	ds_read_b128 v[224:227], v241 offset:16384
	ds_read_b128 v[228:231], v241 offset:17408
	ds_read_b128 v[232:235], v241 offset:18432
	ds_read_b128 v[236:239], v241 offset:19456
	ds_read_b128 v[212:215], v240 offset:17408
	ds_read_b128 v[216:219], v240 offset:18432
	ds_read_b128 v[220:223], v240 offset:19456
	s_waitcnt lgkmcnt(6)
	v_mfma_f32_16x16x32_bf16 v[2:5], v[224:227], v[208:211], v[2:5]
	s_waitcnt lgkmcnt(5)
	v_mfma_f32_16x16x32_bf16 v[6:9], v[228:231], v[208:211], v[6:9]
	s_waitcnt lgkmcnt(4)
	v_mfma_f32_16x16x32_bf16 v[10:13], v[232:235], v[208:211], v[10:13]
	s_waitcnt lgkmcnt(3)
	v_mfma_f32_16x16x32_bf16 v[14:17], v[236:239], v[208:211], v[14:17]
	s_waitcnt lgkmcnt(2)
	v_mfma_f32_16x16x32_bf16 v[18:21], v[224:227], v[212:215], v[18:21]
	v_mfma_f32_16x16x32_bf16 v[22:25], v[228:231], v[212:215], v[22:25]
	v_mfma_f32_16x16x32_bf16 v[26:29], v[232:235], v[212:215], v[26:29]
	v_mfma_f32_16x16x32_bf16 v[30:33], v[236:239], v[212:215], v[30:33]
	s_waitcnt lgkmcnt(1)
	v_mfma_f32_16x16x32_bf16 v[34:37], v[224:227], v[216:219], v[34:37]
	v_mfma_f32_16x16x32_bf16 v[38:41], v[228:231], v[216:219], v[38:41]
	v_mfma_f32_16x16x32_bf16 v[42:45], v[232:235], v[216:219], v[42:45]
	v_mfma_f32_16x16x32_bf16 v[46:49], v[236:239], v[216:219], v[46:49]
	s_waitcnt lgkmcnt(0)
	v_mfma_f32_16x16x32_bf16 v[50:53], v[224:227], v[220:223], v[50:53]
	v_mfma_f32_16x16x32_bf16 v[54:57], v[228:231], v[220:223], v[54:57]
	v_mfma_f32_16x16x32_bf16 v[58:61], v[232:235], v[220:223], v[58:61]
	v_mfma_f32_16x16x32_bf16 v[62:65], v[236:239], v[220:223], v[62:65]
	s_waitcnt vmcnt(4)
	s_barrier
; #define BLOAD(A_, B_, kt) do { _Pragma("unroll") for (int i = 0; i < 4; ++i) { \
;     A_[i] = *(const u32x4*)((const char*)Ap + (aoff + (unsigned)(32 * i * lda + (kt) * 64) * 2u)); B_[i] = *(const u32x4*)((const char*)Wt + (woff + (unsigned)(32 * i * K + (kt) * 64) * 2u)); } } while (0)
; #define BLOAD(A_, B_, kt) do { _Pragma("unroll") for (int i = 0; i < 4; ++i) { \
;     A_[i] = *(const u32x4*)((const char*)Ap + (aoff + (unsigned)(32 * i * lda + (kt) * 64) * 2u)); B_[i] = *(const u32x4*)((const char*)Wt + (woff + (unsigned)(32 * i * K + (kt) * 64) * 2u)); } } while (0)
; #define BSTORE(A_, B_, buf) do { _Pragma("unroll") for (int i = 0; i < 4; ++i) { \
;     *(u32x4*)&As[(buf) * GBUF + (srow + 32 * i) * LDT + sc8] = A_[i]; \
;     *(u32x4*)&Bs[(buf) * GBUF + (srow + 32 * i) * LDT + sc8] = B_[i]; } } while (0)
; template <bool ROWNORM, int NK>
; DI void gemm_main_bf(const u16* __restrict__ Ap, int lda, const u16* __restrict__ Wt, f32x16 (&acc)[2][2], char* smem, float* rinv_s) {
;     ...
; #pragma unroll
;   for (int kt = 0; kt < nk; kt += 2) {
;     BCOMP(0);
;     BSTORE(a1, b1, 1);
;     if (kt + 3 < nk) BLOAD(a1, b1, kt + 3);
;     __syncthreads();
;     BCOMP(1);
;     if (kt + 2 < nk) { BSTORE(a0, b0, 0); if (kt + 4 < nk) BLOAD(a0, b0, kt + 4); }
;     __syncthreads();
;   }
; DI void tile_branch(const Params& p, int l, int tile, char* smem) {
;     ...
;   for (int br = 0; br < 3; ++br) {
;     unsigned gpk[2][2][8];
;     {
;       f32x16 accg[2][2]; zero_acc(accg);
;       gemm_main_bf<false, 16>((const u16*)(p.ws + OFF_XB) + (size_t)m0 * 1024, 1024,
;                               (const u16*)(p.ws + OFF_WIN + l * SZ_WIN) + (size_t)(5760 + br * 1024 + n0) * 1024, accg, smem, nullptr);
	ds_read_b128 v[208:211], v240 offset:32768
	ds_read_b128 v[224:227], v241 offset:32768
	ds_read_b128 v[228:231], v241 offset:33792
	ds_read_b128 v[232:235], v241 offset:34816
	ds_read_b128 v[236:239], v241 offset:35840
	ds_read_b128 v[212:215], v240 offset:33792
	ds_read_b128 v[216:219], v240 offset:34816
	ds_read_b128 v[220:223], v240 offset:35840
	s_waitcnt lgkmcnt(6)
	v_mfma_f32_16x16x32_bf16 v[2:5], v[224:227], v[208:211], v[2:5]
	s_waitcnt lgkmcnt(5)
	v_mfma_f32_16x16x32_bf16 v[6:9], v[228:231], v[208:211], v[6:9]
	s_waitcnt lgkmcnt(4)
	v_mfma_f32_16x16x32_bf16 v[10:13], v[232:235], v[208:211], v[10:13]
	s_waitcnt lgkmcnt(3)
	v_mfma_f32_16x16x32_bf16 v[14:17], v[236:239], v[208:211], v[14:17]
	s_waitcnt lgkmcnt(2)
	v_mfma_f32_16x16x32_bf16 v[18:21], v[224:227], v[212:215], v[18:21]
	v_mfma_f32_16x16x32_bf16 v[22:25], v[228:231], v[212:215], v[22:25]
	v_mfma_f32_16x16x32_bf16 v[26:29], v[232:235], v[212:215], v[26:29]
	v_mfma_f32_16x16x32_bf16 v[30:33], v[236:239], v[212:215], v[30:33]
	s_waitcnt lgkmcnt(1)
	v_mfma_f32_16x16x32_bf16 v[34:37], v[224:227], v[216:219], v[34:37]
	v_mfma_f32_16x16x32_bf16 v[38:41], v[228:231], v[216:219], v[38:41]
	v_mfma_f32_16x16x32_bf16 v[42:45], v[232:235], v[216:219], v[42:45]
	v_mfma_f32_16x16x32_bf16 v[46:49], v[236:239], v[216:219], v[46:49]
	s_waitcnt lgkmcnt(0)
	v_mfma_f32_16x16x32_bf16 v[50:53], v[224:227], v[220:223], v[50:53]
	v_mfma_f32_16x16x32_bf16 v[54:57], v[228:231], v[220:223], v[54:57]
	v_mfma_f32_16x16x32_bf16 v[58:61], v[232:235], v[220:223], v[58:61]
	v_mfma_f32_16x16x32_bf16 v[62:65], v[236:239], v[220:223], v[62:65]
	s_waitcnt vmcnt(0)
	s_barrier
	ds_read_b128 v[208:211], v240 offset:49152
	ds_read_b128 v[224:227], v241 offset:49152
	ds_read_b128 v[228:231], v241 offset:50176
	ds_read_b128 v[232:235], v241 offset:51200
	ds_read_b128 v[236:239], v241 offset:52224
	ds_read_b128 v[212:215], v240 offset:50176
	ds_read_b128 v[216:219], v240 offset:51200
	ds_read_b128 v[220:223], v240 offset:52224
	s_waitcnt lgkmcnt(6)
	v_mfma_f32_16x16x32_bf16 v[2:5], v[224:227], v[208:211], v[2:5]
	s_waitcnt lgkmcnt(5)
	v_mfma_f32_16x16x32_bf16 v[6:9], v[228:231], v[208:211], v[6:9]
	s_waitcnt lgkmcnt(4)
	v_mfma_f32_16x16x32_bf16 v[10:13], v[232:235], v[208:211], v[10:13]
	s_waitcnt lgkmcnt(3)
	v_mfma_f32_16x16x32_bf16 v[14:17], v[236:239], v[208:211], v[14:17]
	s_waitcnt lgkmcnt(2)
	v_mfma_f32_16x16x32_bf16 v[18:21], v[224:227], v[212:215], v[18:21]
	v_mfma_f32_16x16x32_bf16 v[22:25], v[228:231], v[212:215], v[22:25]
	v_mfma_f32_16x16x32_bf16 v[26:29], v[232:235], v[212:215], v[26:29]
	v_mfma_f32_16x16x32_bf16 v[30:33], v[236:239], v[212:215], v[30:33]
	s_waitcnt lgkmcnt(1)
	v_mfma_f32_16x16x32_bf16 v[34:37], v[224:227], v[216:219], v[34:37]
	v_mfma_f32_16x16x32_bf16 v[38:41], v[228:231], v[216:219], v[38:41]
	v_mfma_f32_16x16x32_bf16 v[42:45], v[232:235], v[216:219], v[42:45]
	v_mfma_f32_16x16x32_bf16 v[46:49], v[236:239], v[216:219], v[46:49]
	s_waitcnt lgkmcnt(0)
	v_mfma_f32_16x16x32_bf16 v[50:53], v[224:227], v[220:223], v[50:53]
	v_mfma_f32_16x16x32_bf16 v[54:57], v[228:231], v[220:223], v[54:57]
	v_mfma_f32_16x16x32_bf16 v[58:61], v[232:235], v[220:223], v[58:61]
	v_mfma_f32_16x16x32_bf16 v[62:65], v[236:239], v[220:223], v[62:65]
	s_add_u32 s46, s46, 0x10000
	s_addc_u32 s47, s47, 0
	s_add_u32 s48, s48, 0x1000000
	s_addc_u32 s49, s49, 0
	s_add_u32 s50, s50, 0x100000
	s_addc_u32 s51, s51, 0
	s_cmp_eq_u32 s75, 2
	s_cbranch_scc1 .Lbr_noprol
	s_mov_b64 s[28:29], s[44:45]
	s_mov_b64 s[30:31], s[46:47]
	s_add_u32 m0, s52, 0x0
	s_nop 0
	global_load_lds_dwordx4 v242, s[28:29]
	global_load_lds_dwordx4 v243, s[28:29] offset:1024
	s_add_u32 m0, s53, 0x0
	s_nop 0
	global_load_lds_dwordx4 v251, s[30:31]
	global_load_lds_dwordx4 v251, s[30:31] offset:1024
	s_add_u32 m0, s52, 0x4000
	s_add_u32 s28, s28, 0x40
	s_addc_u32 s29, s29, 0
	global_load_lds_dwordx4 v242, s[28:29]
	global_load_lds_dwordx4 v243, s[28:29] offset:1024
	s_add_u32 m0, s53, 0x4000
	s_add_u32 s30, s30, 0x30000
	s_addc_u32 s31, s31, 0
	global_load_lds_dwordx4 v251, s[30:31]
	global_load_lds_dwordx4 v251, s[30:31] offset:1024
	s_add_u32 m0, s52, 0x8000
	s_add_u32 s28, s28, 0x40
	s_addc_u32 s29, s29, 0
	global_load_lds_dwordx4 v242, s[28:29]
	global_load_lds_dwordx4 v243, s[28:29] offset:1024
	s_add_u32 m0, s53, 0x8000
	s_add_u32 s30, s30, 0x30000
	s_addc_u32 s31, s31, 0
	global_load_lds_dwordx4 v251, s[30:31]
	global_load_lds_dwordx4 v251, s[30:31] offset:1024
